# GEMM loops: saddr form for LDS-DMA loads with scalar base, removing the per-load 64-bit VALU address add
# baseline (speedup 1.0000x reference)
; #define PG8_STAGE(bufoff, gbase, voff) do { _Pragma("unroll") for (int _i = 0; _i < 2; ++_i) \
;         __builtin_amdgcn_global_load_lds((const unsigned*)((const char*)(gbase) + (voff)[_i]), (PG8_LAS unsigned*)(lds + (bufoff) + ldsw + _i * 8192), 16, 0, 0); } while (0)
; #define PG8_LDA(dst, b, h) do { _Pragma("unroll") for (int m = 0; m < 4; ++m) _Pragma("unroll") for (int k = 0; k < 2; ++k) dst[m][k] = *(const PG8_LAS bf16x8*)(lds + PG8_SA(b, h) + aoff + m * 2048 + k * 1024); } while (0)
; #define PG8_LDB(dst, b, h) do { _Pragma("unroll") for (int n = 0; n < 2; ++n) _Pragma("unroll") for (int k = 0; k < 2; ++k) dst[n][k] = *(const PG8_LAS bf16x8*)(lds + PG8_SB(b, h) + boff + n * 2048 + k * 1024); } while (0)
; #define PG8_MMA(ai, bj, At, Bt) do { __builtin_amdgcn_s_setprio(1); _Pragma("unroll") for (int m = 0; m < 4; ++m) _Pragma("unroll") for (int n = 0; n < 2; ++n) _Pragma("unroll") for (int k = 0; k < 2; ++k) \
;         acc[ai][bj][m][n] = __builtin_amdgcn_mfma_f32_16x16x32_bf16(Bt[n][k], At[m][k], acc[ai][bj][m][n], 0, 0, 0); __builtin_amdgcn_s_setprio(0); } while (0)
; #define PG8_WAIT_V(n) asm volatile("s_waitcnt vmcnt(" #n ")" ::: "memory")
; #define PG8_WAIT_L(n) asm volatile("s_waitcnt lgkmcnt(" #n ")" ::: "memory")
; #define PG8_BAR __builtin_amdgcn_s_barrier()
; #define PG8_SCHED __builtin_amdgcn_sched_barrier(0)
;     ...
;             const bool last = (t == nt - 2);
;             const char* a1 = cA + (size_t)(t + 1) * kstep;
;             const char* a2 = last ? nA : cA + (size_t)(t + 2) * kstep; const char* b2 = last ? nB : cB + (size_t)(t + 2) * kstep;
;             const char* a3 = a2 + kstep; const char* b3 = b2 + kstep;
;             if (last && has_next) S.a_ready(nxt);
;             if constexpr (SP2) {
;             PG8_LDB(B0, 0, 0); PG8_LDB(B1, 0, 1); PG8_SCHED; PG8_LDA(At, 0, 0); PG8_STAGE(PG8_SA(1, 1), a1 + hstepA, voffA);
;             PG8_WAIT_V(8); PG8_WAIT_L(0); PG8_BAR; PG8_MMA(0, 0, At, B0); PG8_MMA(0, 1, At, B1); PG8_BAR; PG8_SCHED;
;             PG8_LDA(At, 0, 1); PG8_STAGE(PG8_SB(0, 0), b2, voffB); PG8_STAGE(PG8_SB(0, 1), b2 + hstep, voffB); PG8_STAGE(PG8_SA(0, 0), a2, voffA);
;             PG8_WAIT_V(8); PG8_WAIT_L(0); PG8_BAR; PG8_MMA(1, 0, At, B0); PG8_MMA(1, 1, At, B1); PG8_BAR; PG8_SCHED;
.LBB0_407:
	s_add_u32 s28, s30, 0xfff80080
	s_addc_u32 s29, s31, -1
	s_add_i32 s42, 0, 0x10000
	s_cmp_eq_u32 s93, 28
	s_cselect_b32 vcc_hi, s9, s29
	s_cselect_b32 vcc_lo, s25, s28
	v_add_u32_e32 v32, s42, v180
	s_cselect_b32 s29, s33, s50
	s_cselect_b32 s28, s40, s48
	s_add_i32 s46, 0, 0x14000
	ds_read_b128 v[136:139], v32
	ds_read_b128 v[140:143], v32 offset:1024
	ds_read_b128 v[144:147], v32 offset:2048
	ds_read_b128 v[148:151], v32 offset:3072
	v_add_u32_e32 v32, s46, v180
	ds_read_b128 v[166:169], v32
	ds_read_b128 v[170:173], v32 offset:1024
	ds_read_b128 v[174:177], v32 offset:2048
	ds_read_b128 v[198:201], v32 offset:3072
	s_add_i32 m0, s17, 0xc000
	ds_read_b128 v[202:205], v196
	ds_read_b128 v[206:209], v196 offset:1024
	ds_read_b128 v[210:213], v196 offset:2048
	ds_read_b128 v[214:217], v196 offset:3072
	ds_read_b128 v[218:221], v196 offset:4096
	ds_read_b128 v[222:225], v196 offset:5120
	ds_read_b128 v[226:229], v196 offset:6144
	ds_read_b128 v[240:243], v196 offset:7168
	global_load_lds_dwordx4 v162, s[30:31]
	s_add_i32 m0, s17, 0xe000
	s_nop 0
	global_load_lds_dwordx4 v164, s[30:31]
	s_waitcnt vmcnt(8)
	s_waitcnt lgkmcnt(0)
	s_barrier
	s_setprio 1
	s_waitcnt lgkmcnt(0)
	v_mfma_f32_16x16x32_bf16 v[132:135], v[136:139], v[202:205], v[132:135]
	v_mfma_f32_16x16x32_bf16 v[132:135], v[140:143], v[206:209], v[132:135]
	v_mfma_f32_16x16x32_bf16 v[128:131], v[148:151], v[206:209], v[128:131]
	v_mfma_f32_16x16x32_bf16 v[128:131], v[144:147], v[202:205], v[128:131]
	v_mfma_f32_16x16x32_bf16 v[112:115], v[144:147], v[210:213], v[112:115]
	v_mfma_f32_16x16x32_bf16 v[112:115], v[148:151], v[214:217], v[112:115]
	v_mfma_f32_16x16x32_bf16 v[116:119], v[140:143], v[214:217], v[116:119]
	v_mfma_f32_16x16x32_bf16 v[116:119], v[136:139], v[210:213], v[116:119]
	v_mfma_f32_16x16x32_bf16 v[100:103], v[136:139], v[218:221], v[100:103]
	v_mfma_f32_16x16x32_bf16 v[100:103], v[140:143], v[222:225], v[100:103]
	v_mfma_f32_16x16x32_bf16 v[96:99], v[148:151], v[222:225], v[96:99]
	v_mfma_f32_16x16x32_bf16 v[96:99], v[144:147], v[218:221], v[96:99]
	v_mfma_f32_16x16x32_bf16 v[80:83], v[144:147], v[226:229], v[80:83]
	v_mfma_f32_16x16x32_bf16 v[80:83], v[148:151], v[240:243], v[80:83]
	v_mfma_f32_16x16x32_bf16 v[84:87], v[140:143], v[240:243], v[84:87]
	v_mfma_f32_16x16x32_bf16 v[84:87], v[136:139], v[226:229], v[84:87]
	s_setprio 0
	s_setprio 1
	v_mfma_f32_16x16x32_bf16 v[124:127], v[166:169], v[202:205], v[124:127]
	v_mfma_f32_16x16x32_bf16 v[124:127], v[170:173], v[206:209], v[124:127]
	v_mfma_f32_16x16x32_bf16 v[120:123], v[198:201], v[206:209], v[120:123]
	v_mfma_f32_16x16x32_bf16 v[120:123], v[174:177], v[202:205], v[120:123]
	v_mfma_f32_16x16x32_bf16 v[104:107], v[174:177], v[210:213], v[104:107]
	v_mfma_f32_16x16x32_bf16 v[104:107], v[198:201], v[214:217], v[104:107]
	v_mfma_f32_16x16x32_bf16 v[108:111], v[170:173], v[214:217], v[108:111]
	v_mfma_f32_16x16x32_bf16 v[108:111], v[166:169], v[210:213], v[108:111]
	v_mfma_f32_16x16x32_bf16 v[92:95], v[166:169], v[218:221], v[92:95]
	v_mfma_f32_16x16x32_bf16 v[92:95], v[170:173], v[222:225], v[92:95]
	v_mfma_f32_16x16x32_bf16 v[88:91], v[198:201], v[222:225], v[88:91]
	v_mfma_f32_16x16x32_bf16 v[88:91], v[174:177], v[218:221], v[88:91]
	v_mfma_f32_16x16x32_bf16 v[72:75], v[174:177], v[226:229], v[72:75]
	v_mfma_f32_16x16x32_bf16 v[72:75], v[198:201], v[240:243], v[72:75]
	v_mfma_f32_16x16x32_bf16 v[76:79], v[170:173], v[240:243], v[76:79]
	v_mfma_f32_16x16x32_bf16 v[76:79], v[166:169], v[226:229], v[76:79]
	s_setprio 0
	s_barrier
	s_add_i32 s42, s42, s41
	v_lshl_add_u64 v[178:179], s[28:29], 0, v[154:155]
	s_mov_b32 m0, s42
	ds_read_b128 v[202:205], v196 offset:16384
	ds_read_b128 v[206:209], v196 offset:17408
	ds_read_b128 v[210:213], v196 offset:18432
	ds_read_b128 v[214:217], v196 offset:19456
	ds_read_b128 v[218:221], v196 offset:20480
	ds_read_b128 v[222:225], v196 offset:21504
	ds_read_b128 v[226:229], v196 offset:22528
	ds_read_b128 v[240:243], v196 offset:23552
	global_load_lds_dwordx4 v[178:179], off
	s_add_i32 m0, s42, 0x2000
	s_add_u32 s42, s28, 0x80000
	v_lshl_add_u64 v[186:187], s[28:29], 0, v[158:159]
	s_addc_u32 s43, s29, 0
	s_add_i32 s46, s46, s41
	global_load_lds_dwordx4 v[186:187], off
	s_mov_b32 m0, s46
	v_lshl_add_u64 v[188:189], vcc, 0, v[152:153]
	global_load_lds_dwordx4 v154, s[42:43]
	v_lshl_add_u64 v[34:35], s[42:43], 0, v[158:159]
	s_add_i32 m0, s46, 0x2000
	v_lshl_add_u64 v[190:191], vcc, 0, v[156:157]
	global_load_lds_dwordx4 v[34:35], off
	s_mov_b32 m0, s17
	s_nop 0
	global_load_lds_dwordx4 v[188:189], off
	s_mov_b32 m0, s53
	s_nop 0
	global_load_lds_dwordx4 v[190:191], off
	s_waitcnt vmcnt(8)
	s_waitcnt lgkmcnt(0)
	s_barrier
; #define PG8_STAGE(bufoff, gbase, voff) do { _Pragma("unroll") for (int _i = 0; _i < 2; ++_i) \
;         __builtin_amdgcn_global_load_lds((const unsigned*)((const char*)(gbase) + (voff)[_i]), (PG8_LAS unsigned*)(lds + (bufoff) + ldsw + _i * 8192), 16, 0, 0); } while (0)
; #define PG8_LDA(dst, b, h) do { _Pragma("unroll") for (int m = 0; m < 4; ++m) _Pragma("unroll") for (int k = 0; k < 2; ++k) dst[m][k] = *(const PG8_LAS bf16x8*)(lds + PG8_SA(b, h) + aoff + m * 2048 + k * 1024); } while (0)
; #define PG8_LDB(dst, b, h) do { _Pragma("unroll") for (int n = 0; n < 2; ++n) _Pragma("unroll") for (int k = 0; k < 2; ++k) dst[n][k] = *(const PG8_LAS bf16x8*)(lds + PG8_SB(b, h) + boff + n * 2048 + k * 1024); } while (0)
; #define PG8_MMA(ai, bj, At, Bt) do { __builtin_amdgcn_s_setprio(1); _Pragma("unroll") for (int m = 0; m < 4; ++m) _Pragma("unroll") for (int n = 0; n < 2; ++n) _Pragma("unroll") for (int k = 0; k < 2; ++k) \
;         acc[ai][bj][m][n] = __builtin_amdgcn_mfma_f32_16x16x32_bf16(Bt[n][k], At[m][k], acc[ai][bj][m][n], 0, 0, 0); __builtin_amdgcn_s_setprio(0); } while (0)
; #define PG8_WAIT_V(n) asm volatile("s_waitcnt vmcnt(" #n ")" ::: "memory")
; #define PG8_WAIT_L(n) asm volatile("s_waitcnt lgkmcnt(" #n ")" ::: "memory")
; #define PG8_BAR __builtin_amdgcn_s_barrier()
; #define PG8_SCHED __builtin_amdgcn_sched_barrier(0)
;     ...
;             PG8_WAIT_V(8); PG8_WAIT_L(0); PG8_BAR; PG8_MMA(1, 0, At, B0); PG8_MMA(1, 1, At, B1); PG8_BAR; PG8_SCHED;
;             PG8_LDB(B0, 1, 0); PG8_LDB(B1, 1, 1); PG8_SCHED; PG8_LDA(At, 1, 0); PG8_STAGE(PG8_SA(0, 1), a2 + hstepA, voffA);
;             PG8_WAIT_V(8); PG8_WAIT_L(0); PG8_BAR; PG8_MMA(0, 0, At, B0); PG8_MMA(0, 1, At, B1); PG8_BAR; PG8_SCHED;
	s_setprio 1
	s_waitcnt lgkmcnt(0)
	v_mfma_f32_16x16x32_bf16 v[68:71], v[136:139], v[202:205], v[68:71]
	v_mfma_f32_16x16x32_bf16 v[68:71], v[140:143], v[206:209], v[68:71]
	v_mfma_f32_16x16x32_bf16 v[64:67], v[148:151], v[206:209], v[64:67]
	v_mfma_f32_16x16x32_bf16 v[64:67], v[144:147], v[202:205], v[64:67]
	v_mfma_f32_16x16x32_bf16 v[48:51], v[144:147], v[210:213], v[48:51]
	v_mfma_f32_16x16x32_bf16 v[48:51], v[148:151], v[214:217], v[48:51]
	v_mfma_f32_16x16x32_bf16 v[52:55], v[140:143], v[214:217], v[52:55]
	v_mfma_f32_16x16x32_bf16 v[52:55], v[136:139], v[210:213], v[52:55]
	v_mfma_f32_16x16x32_bf16 v[34:37], v[136:139], v[218:221], v[36:39]
	v_mfma_f32_16x16x32_bf16 v[34:37], v[140:143], v[222:225], v[34:37]
	v_mfma_f32_16x16x32_bf16 v[26:29], v[148:151], v[222:225], v[26:29]
	v_mfma_f32_16x16x32_bf16 v[26:29], v[144:147], v[218:221], v[26:29]
	v_mfma_f32_16x16x32_bf16 v[10:13], v[144:147], v[226:229], v[10:13]
	v_mfma_f32_16x16x32_bf16 v[10:13], v[148:151], v[240:243], v[10:13]
	v_mfma_f32_16x16x32_bf16 v[14:17], v[140:143], v[240:243], v[14:17]
	v_mfma_f32_16x16x32_bf16 v[14:17], v[136:139], v[226:229], v[14:17]
	s_setprio 0
	s_setprio 1
	v_mfma_f32_16x16x32_bf16 v[60:63], v[166:169], v[202:205], v[60:63]
	v_mfma_f32_16x16x32_bf16 v[60:63], v[170:173], v[206:209], v[60:63]
	v_mfma_f32_16x16x32_bf16 v[56:59], v[198:201], v[206:209], v[56:59]
	v_mfma_f32_16x16x32_bf16 v[56:59], v[174:177], v[202:205], v[56:59]
	v_mfma_f32_16x16x32_bf16 v[38:41], v[174:177], v[210:213], v[40:43]
	v_mfma_f32_16x16x32_bf16 v[40:43], v[198:201], v[214:217], v[38:41]
	v_mfma_f32_16x16x32_bf16 v[44:47], v[170:173], v[214:217], v[44:47]
	v_mfma_f32_16x16x32_bf16 v[44:47], v[166:169], v[210:213], v[44:47]
	v_mfma_f32_16x16x32_bf16 v[22:25], v[166:169], v[218:221], v[22:25]
	v_mfma_f32_16x16x32_bf16 v[22:25], v[170:173], v[222:225], v[22:25]
	v_mfma_f32_16x16x32_bf16 v[18:21], v[198:201], v[222:225], v[18:21]
	v_mfma_f32_16x16x32_bf16 v[18:21], v[174:177], v[218:221], v[18:21]
	v_mfma_f32_16x16x32_bf16 v[2:5], v[174:177], v[226:229], v[2:5]
	v_mfma_f32_16x16x32_bf16 v[2:5], v[198:201], v[240:243], v[2:5]
	v_mfma_f32_16x16x32_bf16 v[6:9], v[170:173], v[240:243], v[6:9]
	v_mfma_f32_16x16x32_bf16 v[6:9], v[166:169], v[226:229], v[6:9]
	s_setprio 0
	s_barrier
	s_add_i32 s46, 0, 0x18000
	v_add_u32_e32 v32, s46, v180
	s_add_i32 s47, 0, 0x1c000
	ds_read_b128 v[136:139], v32
	ds_read_b128 v[140:143], v32 offset:1024
	ds_read_b128 v[144:147], v32 offset:2048
	ds_read_b128 v[148:151], v32 offset:3072
	v_add_u32_e32 v32, s47, v180
	ds_read_b128 v[166:169], v32
	ds_read_b128 v[170:173], v32 offset:1024
	ds_read_b128 v[174:177], v32 offset:2048
	ds_read_b128 v[198:201], v32 offset:3072
	s_add_u32 s42, vcc_lo, 0x80000
	s_addc_u32 s43, vcc_hi, 0
	s_mov_b32 m0, s74
	ds_read_b128 v[202:205], v196 offset:32768
	ds_read_b128 v[206:209], v196 offset:33792
	ds_read_b128 v[210:213], v196 offset:34816
	ds_read_b128 v[214:217], v196 offset:35840
	ds_read_b128 v[218:221], v196 offset:36864
	ds_read_b128 v[222:225], v196 offset:37888
	ds_read_b128 v[226:229], v196 offset:38912
	ds_read_b128 v[240:243], v196 offset:39936
	global_load_lds_dwordx4 v152, s[42:43]
	s_mov_b32 m0, s78
	s_nop 0
	global_load_lds_dwordx4 v156, s[42:43]
	s_waitcnt vmcnt(8)
	s_waitcnt lgkmcnt(0)
	s_barrier
	s_setprio 1
	s_waitcnt lgkmcnt(0)
	v_mfma_f32_16x16x32_bf16 v[132:135], v[136:139], v[202:205], v[132:135]
	v_mfma_f32_16x16x32_bf16 v[132:135], v[140:143], v[206:209], v[132:135]
	v_mfma_f32_16x16x32_bf16 v[128:131], v[148:151], v[206:209], v[128:131]
	v_mfma_f32_16x16x32_bf16 v[128:131], v[144:147], v[202:205], v[128:131]
	v_mfma_f32_16x16x32_bf16 v[112:115], v[144:147], v[210:213], v[112:115]
	v_mfma_f32_16x16x32_bf16 v[112:115], v[148:151], v[214:217], v[112:115]
	v_mfma_f32_16x16x32_bf16 v[116:119], v[140:143], v[214:217], v[116:119]
	v_mfma_f32_16x16x32_bf16 v[116:119], v[136:139], v[210:213], v[116:119]
	v_mfma_f32_16x16x32_bf16 v[100:103], v[136:139], v[218:221], v[100:103]
	v_mfma_f32_16x16x32_bf16 v[100:103], v[140:143], v[222:225], v[100:103]
	v_mfma_f32_16x16x32_bf16 v[96:99], v[148:151], v[222:225], v[96:99]
	v_mfma_f32_16x16x32_bf16 v[96:99], v[144:147], v[218:221], v[96:99]
	v_mfma_f32_16x16x32_bf16 v[80:83], v[144:147], v[226:229], v[80:83]
	v_mfma_f32_16x16x32_bf16 v[80:83], v[148:151], v[240:243], v[80:83]
	v_mfma_f32_16x16x32_bf16 v[84:87], v[140:143], v[240:243], v[84:87]
	v_mfma_f32_16x16x32_bf16 v[84:87], v[136:139], v[226:229], v[84:87]
	s_setprio 0
	s_setprio 1
	v_mfma_f32_16x16x32_bf16 v[124:127], v[166:169], v[202:205], v[124:127]
	v_mfma_f32_16x16x32_bf16 v[124:127], v[170:173], v[206:209], v[124:127]
	v_mfma_f32_16x16x32_bf16 v[120:123], v[198:201], v[206:209], v[120:123]
	v_mfma_f32_16x16x32_bf16 v[120:123], v[174:177], v[202:205], v[120:123]
	v_mfma_f32_16x16x32_bf16 v[104:107], v[174:177], v[210:213], v[104:107]
	v_mfma_f32_16x16x32_bf16 v[104:107], v[198:201], v[214:217], v[104:107]
	v_mfma_f32_16x16x32_bf16 v[108:111], v[170:173], v[214:217], v[108:111]
	v_mfma_f32_16x16x32_bf16 v[108:111], v[166:169], v[210:213], v[108:111]
	v_mfma_f32_16x16x32_bf16 v[92:95], v[166:169], v[218:221], v[92:95]
	v_mfma_f32_16x16x32_bf16 v[92:95], v[170:173], v[222:225], v[92:95]
	v_mfma_f32_16x16x32_bf16 v[88:91], v[198:201], v[222:225], v[88:91]
	v_mfma_f32_16x16x32_bf16 v[88:91], v[174:177], v[218:221], v[88:91]
	v_mfma_f32_16x16x32_bf16 v[72:75], v[174:177], v[226:229], v[72:75]
	v_mfma_f32_16x16x32_bf16 v[72:75], v[198:201], v[240:243], v[72:75]
	v_mfma_f32_16x16x32_bf16 v[76:79], v[170:173], v[240:243], v[76:79]
	v_mfma_f32_16x16x32_bf16 v[76:79], v[166:169], v[226:229], v[76:79]
	s_setprio 0
	s_barrier
; #define PG8_STAGE(bufoff, gbase, voff) do { _Pragma("unroll") for (int _i = 0; _i < 2; ++_i) \
;         __builtin_amdgcn_global_load_lds((const unsigned*)((const char*)(gbase) + (voff)[_i]), (PG8_LAS unsigned*)(lds + (bufoff) + ldsw + _i * 8192), 16, 0, 0); } while (0)
; #define PG8_LDA(dst, b, h) do { _Pragma("unroll") for (int m = 0; m < 4; ++m) _Pragma("unroll") for (int k = 0; k < 2; ++k) dst[m][k] = *(const PG8_LAS bf16x8*)(lds + PG8_SA(b, h) + aoff + m * 2048 + k * 1024); } while (0)
; #define PG8_MMA(ai, bj, At, Bt) do { __builtin_amdgcn_s_setprio(1); _Pragma("unroll") for (int m = 0; m < 4; ++m) _Pragma("unroll") for (int n = 0; n < 2; ++n) _Pragma("unroll") for (int k = 0; k < 2; ++k) \
;         acc[ai][bj][m][n] = __builtin_amdgcn_mfma_f32_16x16x32_bf16(Bt[n][k], At[m][k], acc[ai][bj][m][n], 0, 0, 0); __builtin_amdgcn_s_setprio(0); } while (0)
; #define PG8_WAIT_V(n) asm volatile("s_waitcnt vmcnt(" #n ")" ::: "memory")
; #define PG8_WAIT_L(n) asm volatile("s_waitcnt lgkmcnt(" #n ")" ::: "memory")
; #define PG8_BAR __builtin_amdgcn_s_barrier()
; #define PG8_SCHED __builtin_amdgcn_sched_barrier(0)
;     ...
;             PG8_LDA(At, 1, 1); PG8_STAGE(PG8_SB(1, 0), b3, voffB); PG8_STAGE(PG8_SB(1, 1), b3 + hstep, voffB); PG8_STAGE(PG8_SA(1, 0), a3, voffA);
;             PG8_WAIT_V(8); PG8_WAIT_L(0); PG8_BAR; PG8_MMA(1, 0, At, B0); PG8_MMA(1, 1, At, B1); PG8_BAR; PG8_SCHED;
;     ...
;         if constexpr (ALIGN_EPI) { if (wr == 0) PG8_BAR; }
	s_add_i32 s42, s46, s41
	v_lshl_add_u64 v[38:39], v[178:179], 0, s[64:65]
	s_mov_b32 m0, s42
	ds_read_b128 v[202:205], v196 offset:49152
	ds_read_b128 v[206:209], v196 offset:50176
	ds_read_b128 v[210:213], v196 offset:51200
	ds_read_b128 v[214:217], v196 offset:52224
	ds_read_b128 v[218:221], v196 offset:53248
	ds_read_b128 v[222:225], v196 offset:54272
	ds_read_b128 v[226:229], v196 offset:55296
	ds_read_b128 v[240:243], v196 offset:56320
	global_load_lds_dwordx4 v[38:39], off
	s_add_i32 m0, s42, 0x2000
	s_add_u32 s28, s28, 0x80080
	v_lshl_add_u64 v[38:39], v[186:187], 0, s[64:65]
	s_addc_u32 s29, s29, 0
	s_add_i32 s42, s47, s41
	global_load_lds_dwordx4 v[38:39], off
	s_mov_b32 m0, s42
	s_nop 0
	global_load_lds_dwordx4 v154, s[28:29]
	s_add_i32 m0, s42, 0x2000
	s_nop 0
	global_load_lds_dwordx4 v158, s[28:29]
	v_lshl_add_u64 v[38:39], v[188:189], 0, s[64:65]
	s_mov_b32 m0, s79
	s_nop 0
	global_load_lds_dwordx4 v[38:39], off
	v_lshl_add_u64 v[38:39], v[190:191], 0, s[64:65]
	s_mov_b32 m0, s4
	s_nop 0
	global_load_lds_dwordx4 v[38:39], off
	s_waitcnt vmcnt(8)
	s_waitcnt lgkmcnt(0)
	s_barrier
	s_setprio 1
	s_waitcnt lgkmcnt(0)
	v_mfma_f32_16x16x32_bf16 v[68:71], v[136:139], v[202:205], v[68:71]
	v_mfma_f32_16x16x32_bf16 v[68:71], v[140:143], v[206:209], v[68:71]
	v_mfma_f32_16x16x32_bf16 v[64:67], v[148:151], v[206:209], v[64:67]
	v_mfma_f32_16x16x32_bf16 v[64:67], v[144:147], v[202:205], v[64:67]
	v_mfma_f32_16x16x32_bf16 v[48:51], v[144:147], v[210:213], v[48:51]
	v_mfma_f32_16x16x32_bf16 v[48:51], v[148:151], v[214:217], v[48:51]
	v_mfma_f32_16x16x32_bf16 v[52:55], v[140:143], v[214:217], v[52:55]
	v_mfma_f32_16x16x32_bf16 v[52:55], v[136:139], v[210:213], v[52:55]
	v_mfma_f32_16x16x32_bf16 v[34:37], v[136:139], v[218:221], v[34:37]
	v_mfma_f32_16x16x32_bf16 v[36:39], v[140:143], v[222:225], v[34:37]
	v_mfma_f32_16x16x32_bf16 v[26:29], v[148:151], v[222:225], v[26:29]
	v_mfma_f32_16x16x32_bf16 v[26:29], v[144:147], v[218:221], v[26:29]
	v_mfma_f32_16x16x32_bf16 v[10:13], v[144:147], v[226:229], v[10:13]
	v_mfma_f32_16x16x32_bf16 v[10:13], v[148:151], v[240:243], v[10:13]
	v_mfma_f32_16x16x32_bf16 v[14:17], v[140:143], v[240:243], v[14:17]
	v_mfma_f32_16x16x32_bf16 v[14:17], v[136:139], v[226:229], v[14:17]
	s_setprio 0
	s_setprio 1
	v_mfma_f32_16x16x32_bf16 v[60:63], v[166:169], v[202:205], v[60:63]
	v_mfma_f32_16x16x32_bf16 v[60:63], v[170:173], v[206:209], v[60:63]
	v_mfma_f32_16x16x32_bf16 v[56:59], v[198:201], v[206:209], v[56:59]
	v_mfma_f32_16x16x32_bf16 v[56:59], v[174:177], v[202:205], v[56:59]
	v_mfma_f32_16x16x32_bf16 v[40:43], v[174:177], v[210:213], v[40:43]
	v_mfma_f32_16x16x32_bf16 v[40:43], v[198:201], v[214:217], v[40:43]
	v_mfma_f32_16x16x32_bf16 v[44:47], v[170:173], v[214:217], v[44:47]
	v_mfma_f32_16x16x32_bf16 v[44:47], v[166:169], v[210:213], v[44:47]
	v_mfma_f32_16x16x32_bf16 v[22:25], v[166:169], v[218:221], v[22:25]
	v_mfma_f32_16x16x32_bf16 v[22:25], v[170:173], v[222:225], v[22:25]
	v_mfma_f32_16x16x32_bf16 v[18:21], v[198:201], v[222:225], v[18:21]
	v_mfma_f32_16x16x32_bf16 v[18:21], v[174:177], v[218:221], v[18:21]
	v_mfma_f32_16x16x32_bf16 v[2:5], v[174:177], v[226:229], v[2:5]
	v_mfma_f32_16x16x32_bf16 v[2:5], v[198:201], v[240:243], v[2:5]
	v_mfma_f32_16x16x32_bf16 v[6:9], v[170:173], v[240:243], v[6:9]
	v_mfma_f32_16x16x32_bf16 v[6:9], v[166:169], v[226:229], v[6:9]
	s_setprio 0
	s_barrier
	s_add_i32 s93, s93, 2
	s_add_u32 s30, s30, 0x100
	s_addc_u32 s31, s31, 0
	s_add_u32 s48, s48, 0x100
	s_addc_u32 s50, s50, 0
	s_cmp_gt_u32 s93, 29
	s_cbranch_scc0 .LBB0_407
	s_and_b64 vcc, exec, s[60:61]
	s_cbranch_vccz .LBB0_410
	s_barrier

; #define PG8_STAGE(bufoff, gbase, voff) do { _Pragma("unroll") for (int _i = 0; _i < 2; ++_i) \
;         __builtin_amdgcn_global_load_lds((const unsigned*)((const char*)(gbase) + (voff)[_i]), (PG8_LAS unsigned*)(lds + (bufoff) + ldsw + _i * 8192), 16, 0, 0); } while (0)
; #define PG8_LDA(dst, b, h) do { _Pragma("unroll") for (int m = 0; m < 4; ++m) _Pragma("unroll") for (int k = 0; k < 2; ++k) dst[m][k] = *(const PG8_LAS bf16x8*)(lds + PG8_SA(b, h) + aoff + m * 2048 + k * 1024); } while (0)
; #define PG8_LDB(dst, b, h) do { _Pragma("unroll") for (int n = 0; n < 2; ++n) _Pragma("unroll") for (int k = 0; k < 2; ++k) dst[n][k] = *(const PG8_LAS bf16x8*)(lds + PG8_SB(b, h) + boff + n * 2048 + k * 1024); } while (0)
; #define PG8_MMA(ai, bj, At, Bt) do { __builtin_amdgcn_s_setprio(1); _Pragma("unroll") for (int m = 0; m < 4; ++m) _Pragma("unroll") for (int n = 0; n < 2; ++n) _Pragma("unroll") for (int k = 0; k < 2; ++k) \
;         acc[ai][bj][m][n] = __builtin_amdgcn_mfma_f32_16x16x32_bf16(Bt[n][k], At[m][k], acc[ai][bj][m][n], 0, 0, 0); __builtin_amdgcn_s_setprio(0); } while (0)
; #define PG8_WAIT_V(n) asm volatile("s_waitcnt vmcnt(" #n ")" ::: "memory")
; #define PG8_WAIT_L(n) asm volatile("s_waitcnt lgkmcnt(" #n ")" ::: "memory")
; #define PG8_BAR __builtin_amdgcn_s_barrier()
; #define PG8_SCHED __builtin_amdgcn_sched_barrier(0)
;     ...
;             if constexpr (SP2) {
;             PG8_LDB(B0, 0, 0); PG8_LDB(B1, 0, 1); PG8_SCHED; PG8_LDA(At, 0, 0); PG8_STAGE(PG8_SA(1, 1), a1 + hstepA, voffA);
;             PG8_WAIT_V(8); PG8_WAIT_L(0); PG8_BAR; PG8_MMA(0, 0, At, B0); PG8_MMA(0, 1, At, B1); PG8_BAR; PG8_SCHED;
;             PG8_LDA(At, 0, 1); PG8_STAGE(PG8_SB(0, 0), b2, voffB); PG8_STAGE(PG8_SB(0, 1), b2 + hstep, voffB); PG8_STAGE(PG8_SA(0, 0), a2, voffA);
;             PG8_WAIT_V(8); PG8_WAIT_L(0); PG8_BAR; PG8_MMA(1, 0, At, B0); PG8_MMA(1, 1, At, B1); PG8_BAR; PG8_SCHED;
.LBB0_748:
	s_add_u32 s4, s18, 0x100
	s_addc_u32 s5, s19, 0
	s_add_i32 s42, 0, 0x10000
	s_cmp_eq_u32 s78, 4
	s_cselect_b32 s27, s13, s5
	s_cselect_b32 s26, s12, s4
	v_add_u32_e32 v153, s42, v150
	s_cselect_b32 s25, s11, s74
	s_cselect_b32 s24, s33, s48
	s_add_i32 s43, 0, 0x14000
	ds_read_b128 v[142:145], v153
	ds_read_b128 v[146:149], v153 offset:1024
	ds_read_b128 v[154:157], v153 offset:2048
	ds_read_b128 v[158:161], v153 offset:3072
	v_add_u32_e32 v153, s43, v150
	ds_read_b128 v[162:165], v153
	ds_read_b128 v[166:169], v153 offset:1024
	ds_read_b128 v[170:173], v153 offset:2048
	ds_read_b128 v[174:177], v153 offset:3072
	s_add_i32 m0, s17, 0xc000
	ds_read_b128 v[178:181], v152
	ds_read_b128 v[196:199], v152 offset:1024
	ds_read_b128 v[200:203], v152 offset:2048
	ds_read_b128 v[204:207], v152 offset:3072
	ds_read_b128 v[208:211], v152 offset:4096
	ds_read_b128 v[212:215], v152 offset:5120
	ds_read_b128 v[216:219], v152 offset:6144
	ds_read_b128 v[220:223], v152 offset:7168
	global_load_lds_dwordx4 v138, s[18:19]
	s_add_i32 m0, s17, 0xe000
	s_nop 0
	global_load_lds_dwordx4 v140, s[18:19]
	s_waitcnt vmcnt(8)
	s_waitcnt lgkmcnt(0)
	s_barrier
	s_setprio 1
	s_waitcnt lgkmcnt(0)
	v_mfma_f32_16x16x32_bf16 v[130:133], v[142:145], v[178:181], v[130:133]
	v_mfma_f32_16x16x32_bf16 v[130:133], v[146:149], v[196:199], v[130:133]
	v_mfma_f32_16x16x32_bf16 v[126:129], v[158:161], v[196:199], v[126:129]
	v_mfma_f32_16x16x32_bf16 v[126:129], v[154:157], v[178:181], v[126:129]
	v_mfma_f32_16x16x32_bf16 v[110:113], v[154:157], v[200:203], v[110:113]
	v_mfma_f32_16x16x32_bf16 v[110:113], v[158:161], v[204:207], v[110:113]
	v_mfma_f32_16x16x32_bf16 v[114:117], v[146:149], v[204:207], v[114:117]
	v_mfma_f32_16x16x32_bf16 v[114:117], v[142:145], v[200:203], v[114:117]
	v_mfma_f32_16x16x32_bf16 v[98:101], v[142:145], v[208:211], v[98:101]
	v_mfma_f32_16x16x32_bf16 v[98:101], v[146:149], v[212:215], v[98:101]
	v_mfma_f32_16x16x32_bf16 v[94:97], v[158:161], v[212:215], v[94:97]
	v_mfma_f32_16x16x32_bf16 v[94:97], v[154:157], v[208:211], v[94:97]
	v_mfma_f32_16x16x32_bf16 v[78:81], v[154:157], v[216:219], v[78:81]
	v_mfma_f32_16x16x32_bf16 v[78:81], v[158:161], v[220:223], v[78:81]
	v_mfma_f32_16x16x32_bf16 v[82:85], v[146:149], v[220:223], v[82:85]
	v_mfma_f32_16x16x32_bf16 v[82:85], v[142:145], v[216:219], v[82:85]
	s_setprio 0
	s_setprio 1
	v_mfma_f32_16x16x32_bf16 v[122:125], v[162:165], v[178:181], v[122:125]
	v_mfma_f32_16x16x32_bf16 v[122:125], v[166:169], v[196:199], v[122:125]
	v_mfma_f32_16x16x32_bf16 v[118:121], v[174:177], v[196:199], v[118:121]
	v_mfma_f32_16x16x32_bf16 v[118:121], v[170:173], v[178:181], v[118:121]
	v_mfma_f32_16x16x32_bf16 v[102:105], v[170:173], v[200:203], v[102:105]
	v_mfma_f32_16x16x32_bf16 v[102:105], v[174:177], v[204:207], v[102:105]
	v_mfma_f32_16x16x32_bf16 v[106:109], v[166:169], v[204:207], v[106:109]
	v_mfma_f32_16x16x32_bf16 v[106:109], v[162:165], v[200:203], v[106:109]
	v_mfma_f32_16x16x32_bf16 v[90:93], v[162:165], v[208:211], v[90:93]
	v_mfma_f32_16x16x32_bf16 v[90:93], v[166:169], v[212:215], v[90:93]
	v_mfma_f32_16x16x32_bf16 v[86:89], v[174:177], v[212:215], v[86:89]
	v_mfma_f32_16x16x32_bf16 v[86:89], v[170:173], v[208:211], v[86:89]
	v_mfma_f32_16x16x32_bf16 v[70:73], v[170:173], v[216:219], v[70:73]
	v_mfma_f32_16x16x32_bf16 v[70:73], v[174:177], v[220:223], v[70:73]
	v_mfma_f32_16x16x32_bf16 v[74:77], v[166:169], v[220:223], v[74:77]
	v_mfma_f32_16x16x32_bf16 v[74:77], v[162:165], v[216:219], v[74:77]
	s_setprio 0
	s_barrier
	s_add_i32 s18, s42, s30
	v_lshl_add_u64 v[182:183], s[24:25], 0, v[32:33]
	s_mov_b32 m0, s18
	ds_read_b128 v[178:181], v152 offset:16384
	ds_read_b128 v[196:199], v152 offset:17408
	ds_read_b128 v[200:203], v152 offset:18432
	ds_read_b128 v[204:207], v152 offset:19456
	ds_read_b128 v[208:211], v152 offset:20480
	ds_read_b128 v[212:215], v152 offset:21504
	ds_read_b128 v[216:219], v152 offset:22528
	ds_read_b128 v[220:223], v152 offset:23552
	global_load_lds_dwordx4 v[182:183], off
	s_add_i32 m0, s18, 0x2000
	s_add_u32 s18, s24, 0x20000
	v_lshl_add_u64 v[186:187], s[24:25], 0, v[136:137]
	s_addc_u32 s19, s25, 0
	s_add_i32 s42, s43, s30
	global_load_lds_dwordx4 v[186:187], off
	s_mov_b32 m0, s42
	v_lshl_add_u64 v[190:191], s[26:27], 0, v[134:135]
	global_load_lds_dwordx4 v32, s[18:19]
	s_add_i32 m0, s42, 0x2000
	s_nop 0
	global_load_lds_dwordx4 v136, s[18:19]
	v_lshl_add_u64 v[188:189], s[26:27], 0, v[30:31]
	s_mov_b32 m0, s17
	s_nop 0
	global_load_lds_dwordx4 v[188:189], off
	s_mov_b32 m0, s31
	s_nop 0
	global_load_lds_dwordx4 v[190:191], off
	s_waitcnt vmcnt(8)
	s_waitcnt lgkmcnt(0)
	s_barrier
; #define PG8_STAGE(bufoff, gbase, voff) do { _Pragma("unroll") for (int _i = 0; _i < 2; ++_i) \
;         __builtin_amdgcn_global_load_lds((const unsigned*)((const char*)(gbase) + (voff)[_i]), (PG8_LAS unsigned*)(lds + (bufoff) + ldsw + _i * 8192), 16, 0, 0); } while (0)
; #define PG8_LDA(dst, b, h) do { _Pragma("unroll") for (int m = 0; m < 4; ++m) _Pragma("unroll") for (int k = 0; k < 2; ++k) dst[m][k] = *(const PG8_LAS bf16x8*)(lds + PG8_SA(b, h) + aoff + m * 2048 + k * 1024); } while (0)
; #define PG8_LDB(dst, b, h) do { _Pragma("unroll") for (int n = 0; n < 2; ++n) _Pragma("unroll") for (int k = 0; k < 2; ++k) dst[n][k] = *(const PG8_LAS bf16x8*)(lds + PG8_SB(b, h) + boff + n * 2048 + k * 1024); } while (0)
; #define PG8_MMA(ai, bj, At, Bt) do { __builtin_amdgcn_s_setprio(1); _Pragma("unroll") for (int m = 0; m < 4; ++m) _Pragma("unroll") for (int n = 0; n < 2; ++n) _Pragma("unroll") for (int k = 0; k < 2; ++k) \
;         acc[ai][bj][m][n] = __builtin_amdgcn_mfma_f32_16x16x32_bf16(Bt[n][k], At[m][k], acc[ai][bj][m][n], 0, 0, 0); __builtin_amdgcn_s_setprio(0); } while (0)
; #define PG8_WAIT_V(n) asm volatile("s_waitcnt vmcnt(" #n ")" ::: "memory")
; #define PG8_WAIT_L(n) asm volatile("s_waitcnt lgkmcnt(" #n ")" ::: "memory")
; #define PG8_BAR __builtin_amdgcn_s_barrier()
; #define PG8_SCHED __builtin_amdgcn_sched_barrier(0)
;     ...
;             PG8_WAIT_V(8); PG8_WAIT_L(0); PG8_BAR; PG8_MMA(1, 0, At, B0); PG8_MMA(1, 1, At, B1); PG8_BAR; PG8_SCHED;
;             PG8_LDB(B0, 1, 0); PG8_LDB(B1, 1, 1); PG8_SCHED; PG8_LDA(At, 1, 0); PG8_STAGE(PG8_SA(0, 1), a2 + hstepA, voffA);
;             PG8_WAIT_V(8); PG8_WAIT_L(0); PG8_BAR; PG8_MMA(0, 0, At, B0); PG8_MMA(0, 1, At, B1); PG8_BAR; PG8_SCHED;
	s_setprio 1
	s_waitcnt lgkmcnt(0)
	v_mfma_f32_16x16x32_bf16 v[66:69], v[142:145], v[178:181], v[66:69]
	v_mfma_f32_16x16x32_bf16 v[66:69], v[146:149], v[196:199], v[66:69]
	v_mfma_f32_16x16x32_bf16 v[62:65], v[158:161], v[196:199], v[62:65]
	v_mfma_f32_16x16x32_bf16 v[62:65], v[154:157], v[178:181], v[62:65]
	v_mfma_f32_16x16x32_bf16 v[46:49], v[154:157], v[200:203], v[46:49]
	v_mfma_f32_16x16x32_bf16 v[46:49], v[158:161], v[204:207], v[46:49]
	v_mfma_f32_16x16x32_bf16 v[50:53], v[146:149], v[204:207], v[50:53]
	v_mfma_f32_16x16x32_bf16 v[50:53], v[142:145], v[200:203], v[50:53]
	v_mfma_f32_16x16x32_bf16 v[34:37], v[142:145], v[208:211], v[34:37]
	v_mfma_f32_16x16x32_bf16 v[34:37], v[146:149], v[212:215], v[34:37]
	v_mfma_f32_16x16x32_bf16 v[26:29], v[158:161], v[212:215], v[26:29]
	v_mfma_f32_16x16x32_bf16 v[26:29], v[154:157], v[208:211], v[26:29]
	v_mfma_f32_16x16x32_bf16 v[10:13], v[154:157], v[216:219], v[10:13]
	v_mfma_f32_16x16x32_bf16 v[10:13], v[158:161], v[220:223], v[10:13]
	v_mfma_f32_16x16x32_bf16 v[14:17], v[146:149], v[220:223], v[14:17]
	v_mfma_f32_16x16x32_bf16 v[14:17], v[142:145], v[216:219], v[14:17]
	s_setprio 0
	s_setprio 1
	v_mfma_f32_16x16x32_bf16 v[58:61], v[162:165], v[178:181], v[58:61]
	v_mfma_f32_16x16x32_bf16 v[58:61], v[166:169], v[196:199], v[58:61]
	v_mfma_f32_16x16x32_bf16 v[54:57], v[174:177], v[196:199], v[54:57]
	v_mfma_f32_16x16x32_bf16 v[54:57], v[170:173], v[178:181], v[54:57]
	v_mfma_f32_16x16x32_bf16 v[38:41], v[170:173], v[200:203], v[38:41]
	v_mfma_f32_16x16x32_bf16 v[38:41], v[174:177], v[204:207], v[38:41]
	v_mfma_f32_16x16x32_bf16 v[42:45], v[166:169], v[204:207], v[42:45]
	v_mfma_f32_16x16x32_bf16 v[42:45], v[162:165], v[200:203], v[42:45]
	v_mfma_f32_16x16x32_bf16 v[22:25], v[162:165], v[208:211], v[22:25]
	v_mfma_f32_16x16x32_bf16 v[22:25], v[166:169], v[212:215], v[22:25]
	v_mfma_f32_16x16x32_bf16 v[18:21], v[174:177], v[212:215], v[18:21]
	v_mfma_f32_16x16x32_bf16 v[18:21], v[170:173], v[208:211], v[18:21]
	v_mfma_f32_16x16x32_bf16 v[2:5], v[170:173], v[216:219], v[2:5]
	v_mfma_f32_16x16x32_bf16 v[2:5], v[174:177], v[220:223], v[2:5]
	v_mfma_f32_16x16x32_bf16 v[6:9], v[166:169], v[220:223], v[6:9]
	v_mfma_f32_16x16x32_bf16 v[6:9], v[162:165], v[216:219], v[6:9]
	s_setprio 0
	s_barrier
	s_add_i32 s42, 0, 0x18000
	v_add_u32_e32 v153, s42, v150
	s_add_i32 s43, 0, 0x1c000
	ds_read_b128 v[142:145], v153
	ds_read_b128 v[146:149], v153 offset:1024
	ds_read_b128 v[154:157], v153 offset:2048
	ds_read_b128 v[158:161], v153 offset:3072
	v_add_u32_e32 v153, s43, v150
	ds_read_b128 v[162:165], v153
	ds_read_b128 v[166:169], v153 offset:1024
	ds_read_b128 v[170:173], v153 offset:2048
	ds_read_b128 v[174:177], v153 offset:3072
	s_add_u32 s18, s26, 0xf0000
	s_addc_u32 s19, s27, 0
	s_mov_b32 m0, s38
	ds_read_b128 v[178:181], v152 offset:32768
	ds_read_b128 v[196:199], v152 offset:33792
	ds_read_b128 v[200:203], v152 offset:34816
	ds_read_b128 v[204:207], v152 offset:35840
	ds_read_b128 v[208:211], v152 offset:36864
	ds_read_b128 v[212:215], v152 offset:37888
	ds_read_b128 v[216:219], v152 offset:38912
	ds_read_b128 v[220:223], v152 offset:39936
	global_load_lds_dwordx4 v30, s[18:19]
	v_lshl_add_u64 v[224:225], s[18:19], 0, v[134:135]
	s_mov_b32 m0, s39
	s_nop 0
	global_load_lds_dwordx4 v[224:225], off
	s_waitcnt vmcnt(8)
	s_waitcnt lgkmcnt(0)
	s_barrier
	s_setprio 1
	s_waitcnt lgkmcnt(0)
	v_mfma_f32_16x16x32_bf16 v[130:133], v[142:145], v[178:181], v[130:133]
	v_mfma_f32_16x16x32_bf16 v[130:133], v[146:149], v[196:199], v[130:133]
	v_mfma_f32_16x16x32_bf16 v[126:129], v[158:161], v[196:199], v[126:129]
	v_mfma_f32_16x16x32_bf16 v[126:129], v[154:157], v[178:181], v[126:129]
	v_mfma_f32_16x16x32_bf16 v[110:113], v[154:157], v[200:203], v[110:113]
	v_mfma_f32_16x16x32_bf16 v[110:113], v[158:161], v[204:207], v[110:113]
	v_mfma_f32_16x16x32_bf16 v[114:117], v[146:149], v[204:207], v[114:117]
	v_mfma_f32_16x16x32_bf16 v[114:117], v[142:145], v[200:203], v[114:117]
	v_mfma_f32_16x16x32_bf16 v[98:101], v[142:145], v[208:211], v[98:101]
	v_mfma_f32_16x16x32_bf16 v[98:101], v[146:149], v[212:215], v[98:101]
	v_mfma_f32_16x16x32_bf16 v[94:97], v[158:161], v[212:215], v[94:97]
	v_mfma_f32_16x16x32_bf16 v[94:97], v[154:157], v[208:211], v[94:97]
	v_mfma_f32_16x16x32_bf16 v[78:81], v[154:157], v[216:219], v[78:81]
	v_mfma_f32_16x16x32_bf16 v[78:81], v[158:161], v[220:223], v[78:81]
	v_mfma_f32_16x16x32_bf16 v[82:85], v[146:149], v[220:223], v[82:85]
	v_mfma_f32_16x16x32_bf16 v[82:85], v[142:145], v[216:219], v[82:85]
	s_setprio 0
	s_setprio 1
	v_mfma_f32_16x16x32_bf16 v[122:125], v[162:165], v[178:181], v[122:125]
	v_mfma_f32_16x16x32_bf16 v[122:125], v[166:169], v[196:199], v[122:125]
	v_mfma_f32_16x16x32_bf16 v[118:121], v[174:177], v[196:199], v[118:121]
	v_mfma_f32_16x16x32_bf16 v[118:121], v[170:173], v[178:181], v[118:121]
	v_mfma_f32_16x16x32_bf16 v[102:105], v[170:173], v[200:203], v[102:105]
	v_mfma_f32_16x16x32_bf16 v[102:105], v[174:177], v[204:207], v[102:105]
	v_mfma_f32_16x16x32_bf16 v[106:109], v[166:169], v[204:207], v[106:109]
	v_mfma_f32_16x16x32_bf16 v[106:109], v[162:165], v[200:203], v[106:109]
	v_mfma_f32_16x16x32_bf16 v[90:93], v[162:165], v[208:211], v[90:93]
	v_mfma_f32_16x16x32_bf16 v[90:93], v[166:169], v[212:215], v[90:93]
	v_mfma_f32_16x16x32_bf16 v[86:89], v[174:177], v[212:215], v[86:89]
	v_mfma_f32_16x16x32_bf16 v[86:89], v[170:173], v[208:211], v[86:89]
	v_mfma_f32_16x16x32_bf16 v[70:73], v[170:173], v[216:219], v[70:73]
	v_mfma_f32_16x16x32_bf16 v[70:73], v[174:177], v[220:223], v[70:73]
	v_mfma_f32_16x16x32_bf16 v[74:77], v[166:169], v[220:223], v[74:77]
	v_mfma_f32_16x16x32_bf16 v[74:77], v[162:165], v[216:219], v[74:77]
	s_setprio 0
	s_barrier
; #define PG8_STAGE(bufoff, gbase, voff) do { _Pragma("unroll") for (int _i = 0; _i < 2; ++_i) \
;         __builtin_amdgcn_global_load_lds((const unsigned*)((const char*)(gbase) + (voff)[_i]), (PG8_LAS unsigned*)(lds + (bufoff) + ldsw + _i * 8192), 16, 0, 0); } while (0)
; #define PG8_LDA(dst, b, h) do { _Pragma("unroll") for (int m = 0; m < 4; ++m) _Pragma("unroll") for (int k = 0; k < 2; ++k) dst[m][k] = *(const PG8_LAS bf16x8*)(lds + PG8_SA(b, h) + aoff + m * 2048 + k * 1024); } while (0)
; #define PG8_MMA(ai, bj, At, Bt) do { __builtin_amdgcn_s_setprio(1); _Pragma("unroll") for (int m = 0; m < 4; ++m) _Pragma("unroll") for (int n = 0; n < 2; ++n) _Pragma("unroll") for (int k = 0; k < 2; ++k) \
;         acc[ai][bj][m][n] = __builtin_amdgcn_mfma_f32_16x16x32_bf16(Bt[n][k], At[m][k], acc[ai][bj][m][n], 0, 0, 0); __builtin_amdgcn_s_setprio(0); } while (0)
; #define PG8_WAIT_V(n) asm volatile("s_waitcnt vmcnt(" #n ")" ::: "memory")
; #define PG8_WAIT_L(n) asm volatile("s_waitcnt lgkmcnt(" #n ")" ::: "memory")
; #define PG8_BAR __builtin_amdgcn_s_barrier()
; #define PG8_SCHED __builtin_amdgcn_sched_barrier(0)
;     ...
;         for (int t = 0; t < nt; t += 2) {
;             const bool last = (t == nt - 2);
;             const char* a1 = cA + (size_t)(t + 1) * kstep;
;             const char* a2 = last ? nA : cA + (size_t)(t + 2) * kstep; const char* b2 = last ? nB : cB + (size_t)(t + 2) * kstep;
;     ...
;             PG8_LDA(At, 1, 1); PG8_STAGE(PG8_SB(1, 0), b3, voffB); PG8_STAGE(PG8_SB(1, 1), b3 + hstep, voffB); PG8_STAGE(PG8_SA(1, 0), a3, voffA);
;             PG8_WAIT_V(8); PG8_WAIT_L(0); PG8_BAR; PG8_MMA(1, 0, At, B0); PG8_MMA(1, 1, At, B1); PG8_BAR; PG8_SCHED;
	s_add_i32 s18, s42, s30
	v_lshl_add_u64 v[182:183], v[182:183], 0, s[64:65]
	s_mov_b32 m0, s18
	ds_read_b128 v[178:181], v152 offset:49152
	ds_read_b128 v[196:199], v152 offset:50176
	ds_read_b128 v[200:203], v152 offset:51200
	ds_read_b128 v[204:207], v152 offset:52224
	ds_read_b128 v[208:211], v152 offset:53248
	ds_read_b128 v[212:215], v152 offset:54272
	ds_read_b128 v[216:219], v152 offset:55296
	ds_read_b128 v[220:223], v152 offset:56320
	global_load_lds_dwordx4 v[182:183], off
	s_add_i32 m0, s18, 0x2000
	s_add_u32 s18, s24, 0x20080
	v_lshl_add_u64 v[182:183], v[186:187], 0, s[64:65]
	s_addc_u32 s19, s25, 0
	s_add_i32 s24, s43, s30
	global_load_lds_dwordx4 v[182:183], off
	s_mov_b32 m0, s24
	s_nop 0
	global_load_lds_dwordx4 v32, s[18:19]
	s_add_i32 m0, s24, 0x2000
	s_nop 0
	global_load_lds_dwordx4 v136, s[18:19]
	v_lshl_add_u64 v[182:183], v[188:189], 0, s[64:65]
	s_mov_b32 m0, s40
	s_nop 0
	global_load_lds_dwordx4 v[182:183], off
	v_lshl_add_u64 v[182:183], v[190:191], 0, s[64:65]
	s_mov_b32 m0, s41
	s_nop 0
	global_load_lds_dwordx4 v[182:183], off
	s_waitcnt vmcnt(8)
	s_waitcnt lgkmcnt(0)
	s_barrier
	s_setprio 1
	s_waitcnt lgkmcnt(0)
	v_mfma_f32_16x16x32_bf16 v[66:69], v[142:145], v[178:181], v[66:69]
	v_mfma_f32_16x16x32_bf16 v[66:69], v[146:149], v[196:199], v[66:69]
	v_mfma_f32_16x16x32_bf16 v[62:65], v[158:161], v[196:199], v[62:65]
	v_mfma_f32_16x16x32_bf16 v[62:65], v[154:157], v[178:181], v[62:65]
	v_mfma_f32_16x16x32_bf16 v[46:49], v[154:157], v[200:203], v[46:49]
	v_mfma_f32_16x16x32_bf16 v[46:49], v[158:161], v[204:207], v[46:49]
	v_mfma_f32_16x16x32_bf16 v[50:53], v[146:149], v[204:207], v[50:53]
	v_mfma_f32_16x16x32_bf16 v[50:53], v[142:145], v[200:203], v[50:53]
	v_mfma_f32_16x16x32_bf16 v[34:37], v[142:145], v[208:211], v[34:37]
	v_mfma_f32_16x16x32_bf16 v[34:37], v[146:149], v[212:215], v[34:37]
	v_mfma_f32_16x16x32_bf16 v[26:29], v[158:161], v[212:215], v[26:29]
	v_mfma_f32_16x16x32_bf16 v[26:29], v[154:157], v[208:211], v[26:29]
	v_mfma_f32_16x16x32_bf16 v[10:13], v[154:157], v[216:219], v[10:13]
	v_mfma_f32_16x16x32_bf16 v[10:13], v[158:161], v[220:223], v[10:13]
	v_mfma_f32_16x16x32_bf16 v[14:17], v[146:149], v[220:223], v[14:17]
	v_mfma_f32_16x16x32_bf16 v[14:17], v[142:145], v[216:219], v[14:17]
	s_setprio 0
	s_setprio 1
	v_mfma_f32_16x16x32_bf16 v[58:61], v[162:165], v[178:181], v[58:61]
	v_mfma_f32_16x16x32_bf16 v[58:61], v[166:169], v[196:199], v[58:61]
	v_mfma_f32_16x16x32_bf16 v[54:57], v[174:177], v[196:199], v[54:57]
	v_mfma_f32_16x16x32_bf16 v[54:57], v[170:173], v[178:181], v[54:57]
	v_mfma_f32_16x16x32_bf16 v[38:41], v[170:173], v[200:203], v[38:41]
	v_mfma_f32_16x16x32_bf16 v[38:41], v[174:177], v[204:207], v[38:41]
	v_mfma_f32_16x16x32_bf16 v[42:45], v[166:169], v[204:207], v[42:45]
	v_mfma_f32_16x16x32_bf16 v[42:45], v[162:165], v[200:203], v[42:45]
	v_mfma_f32_16x16x32_bf16 v[22:25], v[162:165], v[208:211], v[22:25]
	v_mfma_f32_16x16x32_bf16 v[22:25], v[166:169], v[212:215], v[22:25]
	v_mfma_f32_16x16x32_bf16 v[18:21], v[174:177], v[212:215], v[18:21]
	v_mfma_f32_16x16x32_bf16 v[18:21], v[170:173], v[208:211], v[18:21]
	v_mfma_f32_16x16x32_bf16 v[2:5], v[170:173], v[216:219], v[2:5]
	v_mfma_f32_16x16x32_bf16 v[2:5], v[174:177], v[220:223], v[2:5]
	v_mfma_f32_16x16x32_bf16 v[6:9], v[166:169], v[220:223], v[6:9]
	v_mfma_f32_16x16x32_bf16 v[6:9], v[162:165], v[216:219], v[6:9]
	s_setprio 0
	s_barrier
	s_add_i32 s78, s78, 2
	s_add_u32 s48, s48, 0x100
	s_addc_u32 s74, s74, 0
	s_cmp_gt_u32 s78, 5
	s_mov_b64 s[18:19], s[4:5]
	s_cbranch_scc0 .LBB0_748
	s_and_b64 vcc, exec, s[8:9]
	s_cbranch_vccz .LBB0_751
	s_barrier

; #define PG8_STAGE(bufoff, gbase, voff) do { _Pragma("unroll") for (int _i = 0; _i < 2; ++_i) \
;         __builtin_amdgcn_global_load_lds((const unsigned*)((const char*)(gbase) + (voff)[_i]), (PG8_LAS unsigned*)(lds + (bufoff) + ldsw + _i * 8192), 16, 0, 0); } while (0)
; #define PG8_LDA(dst, b, h) do { _Pragma("unroll") for (int m = 0; m < 4; ++m) _Pragma("unroll") for (int k = 0; k < 2; ++k) dst[m][k] = *(const PG8_LAS bf16x8*)(lds + PG8_SA(b, h) + aoff + m * 2048 + k * 1024); } while (0)
; #define PG8_LDB(dst, b, h) do { _Pragma("unroll") for (int n = 0; n < 2; ++n) _Pragma("unroll") for (int k = 0; k < 2; ++k) dst[n][k] = *(const PG8_LAS bf16x8*)(lds + PG8_SB(b, h) + boff + n * 2048 + k * 1024); } while (0)
; #define PG8_MMA(ai, bj, At, Bt) do { __builtin_amdgcn_s_setprio(1); _Pragma("unroll") for (int m = 0; m < 4; ++m) _Pragma("unroll") for (int n = 0; n < 2; ++n) _Pragma("unroll") for (int k = 0; k < 2; ++k) \
;         acc[ai][bj][m][n] = __builtin_amdgcn_mfma_f32_16x16x32_bf16(Bt[n][k], At[m][k], acc[ai][bj][m][n], 0, 0, 0); __builtin_amdgcn_s_setprio(0); } while (0)
; #define PG8_WAIT_V(n) asm volatile("s_waitcnt vmcnt(" #n ")" ::: "memory")
; #define PG8_WAIT_L(n) asm volatile("s_waitcnt lgkmcnt(" #n ")" ::: "memory")
; #define PG8_BAR __builtin_amdgcn_s_barrier()
; #define PG8_SCHED __builtin_amdgcn_sched_barrier(0)
;     ...
;             if constexpr (SP2) {
;             PG8_LDB(B0, 0, 0); PG8_LDB(B1, 0, 1); PG8_SCHED; PG8_LDA(At, 0, 0); PG8_STAGE(PG8_SA(1, 1), a1 + hstepA, voffA);
;             PG8_WAIT_V(8); PG8_WAIT_L(0); PG8_BAR; PG8_MMA(0, 0, At, B0); PG8_MMA(0, 1, At, B1); PG8_BAR; PG8_SCHED;
;             PG8_LDA(At, 0, 1); PG8_STAGE(PG8_SB(0, 0), b2, voffB); PG8_STAGE(PG8_SB(0, 1), b2 + hstep, voffB); PG8_STAGE(PG8_SA(0, 0), a2, voffA);
;             PG8_WAIT_V(8); PG8_WAIT_L(0); PG8_BAR; PG8_MMA(1, 0, At, B0); PG8_MMA(1, 1, At, B1); PG8_BAR; PG8_SCHED;
.LBB0_766:
	s_add_u32 s29, s24, s28
	s_addc_u32 s42, s25, 0
	s_add_u32 s30, s29, 0x100
	s_addc_u32 s31, s42, 0
	s_and_b64 s[6:7], s[26:27], exec
	s_cselect_b32 s31, s15, s31
	s_cselect_b32 s30, s14, s30
	s_add_u32 s6, s22, s28
	s_addc_u32 s7, s23, 0
	s_add_u32 s28, s6, 0x100
	s_addc_u32 s38, s7, 0
	s_add_i32 s46, 0, 0x10000
	s_and_b64 s[6:7], s[26:27], exec
	s_cselect_b32 s39, s13, s38
	s_cselect_b32 s38, s33, s28
	s_add_i32 s7, 0, 0x14000
	s_add_u32 s92, s29, 0xf0080
	s_addc_u32 s93, s42, 0
	s_add_i32 s42, s46, s53
	s_add_i32 m0, s19, 0xc000
	s_add_i32 s47, s19, 0xe000
	s_add_i32 s6, s42, 0x2000
	v_add_u32_e32 v149, s46, v146
	s_add_u32 s90, s38, 0x10000
	ds_read_b128 v[138:141], v149
	ds_read_b128 v[142:145], v149 offset:1024
	ds_read_b128 v[150:153], v149 offset:2048
	ds_read_b128 v[154:157], v149 offset:3072
	v_add_u32_e32 v149, s7, v146
	s_addc_u32 s91, s39, 0
	s_add_i32 s43, s7, s53
	ds_read_b128 v[158:161], v149
	ds_read_b128 v[162:165], v149 offset:1024
	ds_read_b128 v[166:169], v149 offset:2048
	ds_read_b128 v[170:173], v149 offset:3072
	s_add_i32 s75, s43, 0x2000
	s_add_i32 vcc_hi, 0, 0x18000
	s_add_i32 s49, 0, 0x1c000
	s_add_u32 s28, s30, 0xf0000
	s_addc_u32 s29, s31, 0
	s_add_i32 vcc_lo, vcc_hi, s53
	s_add_i32 s51, vcc_lo, 0x2000
	s_add_u32 s26, s38, 0x10080
	s_addc_u32 s27, s39, 0
	s_add_i32 s7, s49, s53
	s_add_i32 s46, s7, 0x2000
	ds_read_b128 v[174:177], v148
	ds_read_b128 v[178:181], v148 offset:1024
	ds_read_b128 v[196:199], v148 offset:2048
	ds_read_b128 v[200:203], v148 offset:3072
	ds_read_b128 v[204:207], v148 offset:4096
	ds_read_b128 v[208:211], v148 offset:5120
	ds_read_b128 v[212:215], v148 offset:6144
	ds_read_b128 v[216:219], v148 offset:7168
	global_load_lds_dwordx4 v136, s[92:93]
	s_mov_b32 m0, s47
	s_nop 0
	global_load_lds_dwordx4 v134, s[92:93]
	s_waitcnt vmcnt(8)
	s_waitcnt lgkmcnt(0)
	s_barrier
	s_setprio 1
	s_waitcnt lgkmcnt(0)
	v_mfma_f32_16x16x32_bf16 v[130:133], v[138:141], v[174:177], v[130:133]
	v_mfma_f32_16x16x32_bf16 v[130:133], v[142:145], v[178:181], v[130:133]
	v_mfma_f32_16x16x32_bf16 v[126:129], v[154:157], v[178:181], v[126:129]
	v_mfma_f32_16x16x32_bf16 v[126:129], v[150:153], v[174:177], v[126:129]
	v_mfma_f32_16x16x32_bf16 v[110:113], v[150:153], v[196:199], v[110:113]
	v_mfma_f32_16x16x32_bf16 v[110:113], v[154:157], v[200:203], v[110:113]
	v_mfma_f32_16x16x32_bf16 v[114:117], v[142:145], v[200:203], v[114:117]
	v_mfma_f32_16x16x32_bf16 v[114:117], v[138:141], v[196:199], v[114:117]
	v_mfma_f32_16x16x32_bf16 v[98:101], v[138:141], v[204:207], v[98:101]
	v_mfma_f32_16x16x32_bf16 v[98:101], v[142:145], v[208:211], v[98:101]
	v_mfma_f32_16x16x32_bf16 v[94:97], v[154:157], v[208:211], v[94:97]
	v_mfma_f32_16x16x32_bf16 v[94:97], v[150:153], v[204:207], v[94:97]
	v_mfma_f32_16x16x32_bf16 v[78:81], v[150:153], v[212:215], v[78:81]
	v_mfma_f32_16x16x32_bf16 v[78:81], v[154:157], v[216:219], v[78:81]
	v_mfma_f32_16x16x32_bf16 v[82:85], v[142:145], v[216:219], v[82:85]
	v_mfma_f32_16x16x32_bf16 v[82:85], v[138:141], v[212:215], v[82:85]
	s_setprio 0
	s_setprio 1
	v_mfma_f32_16x16x32_bf16 v[122:125], v[158:161], v[174:177], v[122:125]
	v_mfma_f32_16x16x32_bf16 v[122:125], v[162:165], v[178:181], v[122:125]
	v_mfma_f32_16x16x32_bf16 v[118:121], v[170:173], v[178:181], v[118:121]
	v_mfma_f32_16x16x32_bf16 v[118:121], v[166:169], v[174:177], v[118:121]
	v_mfma_f32_16x16x32_bf16 v[102:105], v[166:169], v[196:199], v[102:105]
	v_mfma_f32_16x16x32_bf16 v[102:105], v[170:173], v[200:203], v[102:105]
	v_mfma_f32_16x16x32_bf16 v[106:109], v[162:165], v[200:203], v[106:109]
	v_mfma_f32_16x16x32_bf16 v[106:109], v[158:161], v[196:199], v[106:109]
	v_mfma_f32_16x16x32_bf16 v[90:93], v[158:161], v[204:207], v[90:93]
	v_mfma_f32_16x16x32_bf16 v[90:93], v[162:165], v[208:211], v[90:93]
	v_mfma_f32_16x16x32_bf16 v[86:89], v[170:173], v[208:211], v[86:89]
	v_mfma_f32_16x16x32_bf16 v[86:89], v[166:169], v[204:207], v[86:89]
	v_mfma_f32_16x16x32_bf16 v[70:73], v[166:169], v[212:215], v[70:73]
	v_mfma_f32_16x16x32_bf16 v[70:73], v[170:173], v[216:219], v[70:73]
	v_mfma_f32_16x16x32_bf16 v[74:77], v[162:165], v[216:219], v[74:77]
	v_mfma_f32_16x16x32_bf16 v[74:77], v[158:161], v[212:215], v[74:77]
	s_setprio 0
	s_barrier
	s_mov_b32 m0, s42
	v_lshl_add_u64 v[182:183], s[38:39], 0, v[32:33]
	ds_read_b128 v[174:177], v148 offset:16384
	ds_read_b128 v[178:181], v148 offset:17408
	ds_read_b128 v[196:199], v148 offset:18432
	ds_read_b128 v[200:203], v148 offset:19456
	ds_read_b128 v[204:207], v148 offset:20480
	ds_read_b128 v[208:211], v148 offset:21504
	ds_read_b128 v[212:215], v148 offset:22528
	ds_read_b128 v[216:219], v148 offset:23552
	global_load_lds_dwordx4 v[182:183], off
	v_lshl_add_u64 v[186:187], s[38:39], 0, v[30:31]
	s_mov_b32 m0, s6
	s_nop 0
	global_load_lds_dwordx4 v[186:187], off
	s_mov_b32 m0, s43
	v_lshl_add_u64 v[190:191], s[30:31], 0, v[134:135]
	global_load_lds_dwordx4 v32, s[90:91]
	s_mov_b32 m0, s75
	s_nop 0
	global_load_lds_dwordx4 v30, s[90:91]
	v_lshl_add_u64 v[188:189], s[30:31], 0, v[136:137]
	s_mov_b32 m0, s19
	s_nop 0
	global_load_lds_dwordx4 v[188:189], off
	s_mov_b32 m0, s74
	s_nop 0
	global_load_lds_dwordx4 v[190:191], off
	s_waitcnt vmcnt(8)
	s_waitcnt lgkmcnt(0)
	s_barrier
; #define PG8_STAGE(bufoff, gbase, voff) do { _Pragma("unroll") for (int _i = 0; _i < 2; ++_i) \
;         __builtin_amdgcn_global_load_lds((const unsigned*)((const char*)(gbase) + (voff)[_i]), (PG8_LAS unsigned*)(lds + (bufoff) + ldsw + _i * 8192), 16, 0, 0); } while (0)
; #define PG8_LDA(dst, b, h) do { _Pragma("unroll") for (int m = 0; m < 4; ++m) _Pragma("unroll") for (int k = 0; k < 2; ++k) dst[m][k] = *(const PG8_LAS bf16x8*)(lds + PG8_SA(b, h) + aoff + m * 2048 + k * 1024); } while (0)
; #define PG8_LDB(dst, b, h) do { _Pragma("unroll") for (int n = 0; n < 2; ++n) _Pragma("unroll") for (int k = 0; k < 2; ++k) dst[n][k] = *(const PG8_LAS bf16x8*)(lds + PG8_SB(b, h) + boff + n * 2048 + k * 1024); } while (0)
; #define PG8_MMA(ai, bj, At, Bt) do { __builtin_amdgcn_s_setprio(1); _Pragma("unroll") for (int m = 0; m < 4; ++m) _Pragma("unroll") for (int n = 0; n < 2; ++n) _Pragma("unroll") for (int k = 0; k < 2; ++k) \
;         acc[ai][bj][m][n] = __builtin_amdgcn_mfma_f32_16x16x32_bf16(Bt[n][k], At[m][k], acc[ai][bj][m][n], 0, 0, 0); __builtin_amdgcn_s_setprio(0); } while (0)
; #define PG8_WAIT_V(n) asm volatile("s_waitcnt vmcnt(" #n ")" ::: "memory")
; #define PG8_WAIT_L(n) asm volatile("s_waitcnt lgkmcnt(" #n ")" ::: "memory")
; #define PG8_BAR __builtin_amdgcn_s_barrier()
; #define PG8_SCHED __builtin_amdgcn_sched_barrier(0)
;     ...
;             PG8_WAIT_V(8); PG8_WAIT_L(0); PG8_BAR; PG8_MMA(1, 0, At, B0); PG8_MMA(1, 1, At, B1); PG8_BAR; PG8_SCHED;
;             PG8_LDB(B0, 1, 0); PG8_LDB(B1, 1, 1); PG8_SCHED; PG8_LDA(At, 1, 0); PG8_STAGE(PG8_SA(0, 1), a2 + hstepA, voffA);
;             PG8_WAIT_V(8); PG8_WAIT_L(0); PG8_BAR; PG8_MMA(0, 0, At, B0); PG8_MMA(0, 1, At, B1); PG8_BAR; PG8_SCHED;
	s_setprio 1
	s_waitcnt lgkmcnt(0)
	v_mfma_f32_16x16x32_bf16 v[66:69], v[138:141], v[174:177], v[66:69]
	v_mfma_f32_16x16x32_bf16 v[66:69], v[142:145], v[178:181], v[66:69]
	v_mfma_f32_16x16x32_bf16 v[62:65], v[154:157], v[178:181], v[62:65]
	v_mfma_f32_16x16x32_bf16 v[62:65], v[150:153], v[174:177], v[62:65]
	v_mfma_f32_16x16x32_bf16 v[46:49], v[150:153], v[196:199], v[46:49]
	v_mfma_f32_16x16x32_bf16 v[46:49], v[154:157], v[200:203], v[46:49]
	v_mfma_f32_16x16x32_bf16 v[50:53], v[142:145], v[200:203], v[50:53]
	v_mfma_f32_16x16x32_bf16 v[50:53], v[138:141], v[196:199], v[50:53]
	v_mfma_f32_16x16x32_bf16 v[34:37], v[138:141], v[204:207], v[34:37]
	v_mfma_f32_16x16x32_bf16 v[34:37], v[142:145], v[208:211], v[34:37]
	v_mfma_f32_16x16x32_bf16 v[26:29], v[154:157], v[208:211], v[26:29]
	v_mfma_f32_16x16x32_bf16 v[26:29], v[150:153], v[204:207], v[26:29]
	v_mfma_f32_16x16x32_bf16 v[10:13], v[150:153], v[212:215], v[10:13]
	v_mfma_f32_16x16x32_bf16 v[10:13], v[154:157], v[216:219], v[10:13]
	v_mfma_f32_16x16x32_bf16 v[14:17], v[142:145], v[216:219], v[14:17]
	v_mfma_f32_16x16x32_bf16 v[14:17], v[138:141], v[212:215], v[14:17]
	s_setprio 0
	s_setprio 1
	v_mfma_f32_16x16x32_bf16 v[58:61], v[158:161], v[174:177], v[58:61]
	v_mfma_f32_16x16x32_bf16 v[58:61], v[162:165], v[178:181], v[58:61]
	v_mfma_f32_16x16x32_bf16 v[54:57], v[170:173], v[178:181], v[54:57]
	v_mfma_f32_16x16x32_bf16 v[54:57], v[166:169], v[174:177], v[54:57]
	v_mfma_f32_16x16x32_bf16 v[38:41], v[166:169], v[196:199], v[38:41]
	v_mfma_f32_16x16x32_bf16 v[38:41], v[170:173], v[200:203], v[38:41]
	v_mfma_f32_16x16x32_bf16 v[42:45], v[162:165], v[200:203], v[42:45]
	v_mfma_f32_16x16x32_bf16 v[42:45], v[158:161], v[196:199], v[42:45]
	v_mfma_f32_16x16x32_bf16 v[22:25], v[158:161], v[204:207], v[22:25]
	v_mfma_f32_16x16x32_bf16 v[22:25], v[162:165], v[208:211], v[22:25]
	v_mfma_f32_16x16x32_bf16 v[18:21], v[170:173], v[208:211], v[18:21]
	v_mfma_f32_16x16x32_bf16 v[18:21], v[166:169], v[204:207], v[18:21]
	v_mfma_f32_16x16x32_bf16 v[2:5], v[166:169], v[212:215], v[2:5]
	v_mfma_f32_16x16x32_bf16 v[2:5], v[170:173], v[216:219], v[2:5]
	v_mfma_f32_16x16x32_bf16 v[6:9], v[162:165], v[216:219], v[6:9]
	v_mfma_f32_16x16x32_bf16 v[6:9], v[158:161], v[212:215], v[6:9]
	s_setprio 0
	s_barrier
	v_add_u32_e32 v149, vcc_hi, v146
	ds_read_b128 v[138:141], v149
	ds_read_b128 v[142:145], v149 offset:1024
	ds_read_b128 v[150:153], v149 offset:2048
	ds_read_b128 v[154:157], v149 offset:3072
	v_add_u32_e32 v149, s49, v146
	ds_read_b128 v[158:161], v149
	ds_read_b128 v[162:165], v149 offset:1024
	ds_read_b128 v[166:169], v149 offset:2048
	ds_read_b128 v[170:173], v149 offset:3072
	s_mov_b32 m0, s78
	ds_read_b128 v[174:177], v148 offset:32768
	ds_read_b128 v[178:181], v148 offset:33792
	ds_read_b128 v[196:199], v148 offset:34816
	ds_read_b128 v[200:203], v148 offset:35840
	ds_read_b128 v[204:207], v148 offset:36864
	ds_read_b128 v[208:211], v148 offset:37888
	ds_read_b128 v[212:215], v148 offset:38912
	ds_read_b128 v[216:219], v148 offset:39936
	global_load_lds_dwordx4 v136, s[28:29]
	v_lshl_add_u64 v[220:221], s[28:29], 0, v[134:135]
	s_mov_b32 m0, s79
	s_nop 0
	global_load_lds_dwordx4 v[220:221], off
	s_waitcnt vmcnt(8)
	s_waitcnt lgkmcnt(0)
	s_barrier
	s_setprio 1
	s_waitcnt lgkmcnt(0)
	v_mfma_f32_16x16x32_bf16 v[130:133], v[138:141], v[174:177], v[130:133]
	v_mfma_f32_16x16x32_bf16 v[130:133], v[142:145], v[178:181], v[130:133]
	v_mfma_f32_16x16x32_bf16 v[126:129], v[154:157], v[178:181], v[126:129]
	v_mfma_f32_16x16x32_bf16 v[126:129], v[150:153], v[174:177], v[126:129]
	v_mfma_f32_16x16x32_bf16 v[110:113], v[150:153], v[196:199], v[110:113]
	v_mfma_f32_16x16x32_bf16 v[110:113], v[154:157], v[200:203], v[110:113]
	v_mfma_f32_16x16x32_bf16 v[114:117], v[142:145], v[200:203], v[114:117]
	v_mfma_f32_16x16x32_bf16 v[114:117], v[138:141], v[196:199], v[114:117]
	v_mfma_f32_16x16x32_bf16 v[98:101], v[138:141], v[204:207], v[98:101]
	v_mfma_f32_16x16x32_bf16 v[98:101], v[142:145], v[208:211], v[98:101]
	v_mfma_f32_16x16x32_bf16 v[94:97], v[154:157], v[208:211], v[94:97]
	v_mfma_f32_16x16x32_bf16 v[94:97], v[150:153], v[204:207], v[94:97]
	v_mfma_f32_16x16x32_bf16 v[78:81], v[150:153], v[212:215], v[78:81]
	v_mfma_f32_16x16x32_bf16 v[78:81], v[154:157], v[216:219], v[78:81]
	v_mfma_f32_16x16x32_bf16 v[82:85], v[142:145], v[216:219], v[82:85]
	v_mfma_f32_16x16x32_bf16 v[82:85], v[138:141], v[212:215], v[82:85]
	s_setprio 0
	s_setprio 1
	v_mfma_f32_16x16x32_bf16 v[122:125], v[158:161], v[174:177], v[122:125]
	v_mfma_f32_16x16x32_bf16 v[122:125], v[162:165], v[178:181], v[122:125]
	v_mfma_f32_16x16x32_bf16 v[118:121], v[170:173], v[178:181], v[118:121]
	v_mfma_f32_16x16x32_bf16 v[118:121], v[166:169], v[174:177], v[118:121]
	v_mfma_f32_16x16x32_bf16 v[102:105], v[166:169], v[196:199], v[102:105]
	v_mfma_f32_16x16x32_bf16 v[102:105], v[170:173], v[200:203], v[102:105]
	v_mfma_f32_16x16x32_bf16 v[106:109], v[162:165], v[200:203], v[106:109]
	v_mfma_f32_16x16x32_bf16 v[106:109], v[158:161], v[196:199], v[106:109]
	v_mfma_f32_16x16x32_bf16 v[90:93], v[158:161], v[204:207], v[90:93]
	v_mfma_f32_16x16x32_bf16 v[90:93], v[162:165], v[208:211], v[90:93]
	v_mfma_f32_16x16x32_bf16 v[86:89], v[170:173], v[208:211], v[86:89]
	v_mfma_f32_16x16x32_bf16 v[86:89], v[166:169], v[204:207], v[86:89]
	v_mfma_f32_16x16x32_bf16 v[70:73], v[166:169], v[212:215], v[70:73]
	v_mfma_f32_16x16x32_bf16 v[70:73], v[170:173], v[216:219], v[70:73]
	v_mfma_f32_16x16x32_bf16 v[74:77], v[162:165], v[216:219], v[74:77]
	v_mfma_f32_16x16x32_bf16 v[74:77], v[158:161], v[212:215], v[74:77]
	s_setprio 0
	s_barrier
; #define PG8_STAGE(bufoff, gbase, voff) do { _Pragma("unroll") for (int _i = 0; _i < 2; ++_i) \
;         __builtin_amdgcn_global_load_lds((const unsigned*)((const char*)(gbase) + (voff)[_i]), (PG8_LAS unsigned*)(lds + (bufoff) + ldsw + _i * 8192), 16, 0, 0); } while (0)
; #define PG8_LDA(dst, b, h) do { _Pragma("unroll") for (int m = 0; m < 4; ++m) _Pragma("unroll") for (int k = 0; k < 2; ++k) dst[m][k] = *(const PG8_LAS bf16x8*)(lds + PG8_SA(b, h) + aoff + m * 2048 + k * 1024); } while (0)
; #define PG8_MMA(ai, bj, At, Bt) do { __builtin_amdgcn_s_setprio(1); _Pragma("unroll") for (int m = 0; m < 4; ++m) _Pragma("unroll") for (int n = 0; n < 2; ++n) _Pragma("unroll") for (int k = 0; k < 2; ++k) \
;         acc[ai][bj][m][n] = __builtin_amdgcn_mfma_f32_16x16x32_bf16(Bt[n][k], At[m][k], acc[ai][bj][m][n], 0, 0, 0); __builtin_amdgcn_s_setprio(0); } while (0)
; #define PG8_WAIT_V(n) asm volatile("s_waitcnt vmcnt(" #n ")" ::: "memory")
; #define PG8_WAIT_L(n) asm volatile("s_waitcnt lgkmcnt(" #n ")" ::: "memory")
; #define PG8_BAR __builtin_amdgcn_s_barrier()
; #define PG8_SCHED __builtin_amdgcn_sched_barrier(0)
;     ...
;         for (int t = 0; t < nt; t += 2) {
;             const bool last = (t == nt - 2);
;             const char* a1 = cA + (size_t)(t + 1) * kstep;
;             const char* a2 = last ? nA : cA + (size_t)(t + 2) * kstep; const char* b2 = last ? nB : cB + (size_t)(t + 2) * kstep;
;     ...
;             PG8_LDA(At, 1, 1); PG8_STAGE(PG8_SB(1, 0), b3, voffB); PG8_STAGE(PG8_SB(1, 1), b3 + hstep, voffB); PG8_STAGE(PG8_SA(1, 0), a3, voffA);
;             PG8_WAIT_V(8); PG8_WAIT_L(0); PG8_BAR; PG8_MMA(1, 0, At, B0); PG8_MMA(1, 1, At, B1); PG8_BAR; PG8_SCHED;
	s_mov_b32 m0, vcc_lo
	v_lshl_add_u64 v[182:183], v[182:183], 0, s[64:65]
	ds_read_b128 v[174:177], v148 offset:49152
	ds_read_b128 v[178:181], v148 offset:50176
	ds_read_b128 v[196:199], v148 offset:51200
	ds_read_b128 v[200:203], v148 offset:52224
	ds_read_b128 v[204:207], v148 offset:53248
	ds_read_b128 v[208:211], v148 offset:54272
	ds_read_b128 v[212:215], v148 offset:55296
	ds_read_b128 v[216:219], v148 offset:56320
	global_load_lds_dwordx4 v[182:183], off
	v_lshl_add_u64 v[182:183], v[186:187], 0, s[64:65]
	s_mov_b32 m0, s51
	s_nop 0
	global_load_lds_dwordx4 v[182:183], off
	s_mov_b32 m0, s7
	s_nop 0
	global_load_lds_dwordx4 v32, s[26:27]
	s_mov_b32 m0, s46
	s_nop 0
	global_load_lds_dwordx4 v30, s[26:27]
	v_lshl_add_u64 v[182:183], v[188:189], 0, s[64:65]
	s_mov_b32 m0, s94
	s_nop 0
	global_load_lds_dwordx4 v[182:183], off
	v_lshl_add_u64 v[182:183], v[190:191], 0, s[64:65]
	s_mov_b32 m0, s95
	s_nop 0
	global_load_lds_dwordx4 v[182:183], off
	s_waitcnt vmcnt(8)
	s_waitcnt lgkmcnt(0)
	s_barrier
	s_setprio 1
	s_waitcnt lgkmcnt(0)
	v_mfma_f32_16x16x32_bf16 v[66:69], v[138:141], v[174:177], v[66:69]
	v_mfma_f32_16x16x32_bf16 v[66:69], v[142:145], v[178:181], v[66:69]
	v_mfma_f32_16x16x32_bf16 v[62:65], v[154:157], v[178:181], v[62:65]
	v_mfma_f32_16x16x32_bf16 v[62:65], v[150:153], v[174:177], v[62:65]
	v_mfma_f32_16x16x32_bf16 v[46:49], v[150:153], v[196:199], v[46:49]
	v_mfma_f32_16x16x32_bf16 v[46:49], v[154:157], v[200:203], v[46:49]
	v_mfma_f32_16x16x32_bf16 v[50:53], v[142:145], v[200:203], v[50:53]
	v_mfma_f32_16x16x32_bf16 v[50:53], v[138:141], v[196:199], v[50:53]
	v_mfma_f32_16x16x32_bf16 v[34:37], v[138:141], v[204:207], v[34:37]
	v_mfma_f32_16x16x32_bf16 v[34:37], v[142:145], v[208:211], v[34:37]
	v_mfma_f32_16x16x32_bf16 v[26:29], v[154:157], v[208:211], v[26:29]
	v_mfma_f32_16x16x32_bf16 v[26:29], v[150:153], v[204:207], v[26:29]
	v_mfma_f32_16x16x32_bf16 v[10:13], v[150:153], v[212:215], v[10:13]
	v_mfma_f32_16x16x32_bf16 v[10:13], v[154:157], v[216:219], v[10:13]
	v_mfma_f32_16x16x32_bf16 v[14:17], v[142:145], v[216:219], v[14:17]
	v_mfma_f32_16x16x32_bf16 v[14:17], v[138:141], v[212:215], v[14:17]
	s_setprio 0
	s_setprio 1
	v_mfma_f32_16x16x32_bf16 v[58:61], v[158:161], v[174:177], v[58:61]
	v_mfma_f32_16x16x32_bf16 v[58:61], v[162:165], v[178:181], v[58:61]
	v_mfma_f32_16x16x32_bf16 v[54:57], v[170:173], v[178:181], v[54:57]
	v_mfma_f32_16x16x32_bf16 v[54:57], v[166:169], v[174:177], v[54:57]
	v_mfma_f32_16x16x32_bf16 v[38:41], v[166:169], v[196:199], v[38:41]
	v_mfma_f32_16x16x32_bf16 v[38:41], v[170:173], v[200:203], v[38:41]
	v_mfma_f32_16x16x32_bf16 v[42:45], v[162:165], v[200:203], v[42:45]
	v_mfma_f32_16x16x32_bf16 v[42:45], v[158:161], v[196:199], v[42:45]
	v_mfma_f32_16x16x32_bf16 v[22:25], v[158:161], v[204:207], v[22:25]
	v_mfma_f32_16x16x32_bf16 v[22:25], v[162:165], v[208:211], v[22:25]
	v_mfma_f32_16x16x32_bf16 v[18:21], v[170:173], v[208:211], v[18:21]
	v_mfma_f32_16x16x32_bf16 v[18:21], v[166:169], v[204:207], v[18:21]
	v_mfma_f32_16x16x32_bf16 v[2:5], v[166:169], v[212:215], v[2:5]
	v_mfma_f32_16x16x32_bf16 v[2:5], v[170:173], v[216:219], v[2:5]
	v_mfma_f32_16x16x32_bf16 v[6:9], v[162:165], v[216:219], v[6:9]
	v_mfma_f32_16x16x32_bf16 v[6:9], v[158:161], v[212:215], v[6:9]
	s_setprio 0
	s_barrier
	s_movk_i32 s28, 0x100
	s_andn2_b64 vcc, exec, s[4:5]
	s_mov_b64 s[26:27], -1
	s_mov_b64 s[4:5], 0
	s_cbranch_vccz .LBB0_766
	s_and_b64 vcc, exec, s[10:11]
	s_cbranch_vccz .LBB0_769
	s_barrier

; #define PG8_STAGE(bufoff, gbase, voff) do { _Pragma("unroll") for (int _i = 0; _i < 2; ++_i) \
;         __builtin_amdgcn_global_load_lds((const unsigned*)((const char*)(gbase) + (voff)[_i]), (PG8_LAS unsigned*)(lds + (bufoff) + ldsw + _i * 8192), 16, 0, 0); } while (0)
; #define PG8_LDA(dst, b, h) do { _Pragma("unroll") for (int m = 0; m < 4; ++m) _Pragma("unroll") for (int k = 0; k < 2; ++k) dst[m][k] = *(const PG8_LAS bf16x8*)(lds + PG8_SA(b, h) + aoff + m * 2048 + k * 1024); } while (0)
; #define PG8_LDB(dst, b, h) do { _Pragma("unroll") for (int n = 0; n < 2; ++n) _Pragma("unroll") for (int k = 0; k < 2; ++k) dst[n][k] = *(const PG8_LAS bf16x8*)(lds + PG8_SB(b, h) + boff + n * 2048 + k * 1024); } while (0)
; #define PG8_MMA(ai, bj, At, Bt) do { __builtin_amdgcn_s_setprio(1); _Pragma("unroll") for (int m = 0; m < 4; ++m) _Pragma("unroll") for (int n = 0; n < 2; ++n) _Pragma("unroll") for (int k = 0; k < 2; ++k) \
;         acc[ai][bj][m][n] = __builtin_amdgcn_mfma_f32_16x16x32_bf16(Bt[n][k], At[m][k], acc[ai][bj][m][n], 0, 0, 0); __builtin_amdgcn_s_setprio(0); } while (0)
; #define PG8_WAIT_V(n) asm volatile("s_waitcnt vmcnt(" #n ")" ::: "memory")
; #define PG8_WAIT_L(n) asm volatile("s_waitcnt lgkmcnt(" #n ")" ::: "memory")
; #define PG8_BAR __builtin_amdgcn_s_barrier()
; #define PG8_SCHED __builtin_amdgcn_sched_barrier(0)
;     ...
;             if constexpr (SP2) {
;             PG8_LDB(B0, 0, 0); PG8_LDB(B1, 0, 1); PG8_SCHED; PG8_LDA(At, 0, 0); PG8_STAGE(PG8_SA(1, 1), a1 + hstepA, voffA);
;             PG8_WAIT_V(8); PG8_WAIT_L(0); PG8_BAR; PG8_MMA(0, 0, At, B0); PG8_MMA(0, 1, At, B1); PG8_BAR; PG8_SCHED;
;             PG8_LDA(At, 0, 1); PG8_STAGE(PG8_SB(0, 0), b2, voffB); PG8_STAGE(PG8_SB(0, 1), b2 + hstep, voffB); PG8_STAGE(PG8_SA(0, 0), a2, voffA);
;             PG8_WAIT_V(8); PG8_WAIT_L(0); PG8_BAR; PG8_MMA(1, 0, At, B0); PG8_MMA(1, 1, At, B1); PG8_BAR; PG8_SCHED;
.LBB0_1064:
	s_add_u32 s30, s28, 0x100
	s_addc_u32 s31, s29, 0
	s_add_i32 s23, 0, 0x10000
	s_cmp_eq_u32 s40, s19
	s_cselect_b32 s93, s91, s31
	s_cselect_b32 s92, s90, s30
	v_add_u32_e32 v32, s23, v239
	s_cselect_b32 s39, s95, s17
	s_cselect_b32 s38, s94, s9
	s_add_i32 s25, 0, 0x14000
	ds_read_b128 v[72:75], v32
	ds_read_b128 v[76:79], v32 offset:1024
	ds_read_b128 v[80:83], v32 offset:2048
	ds_read_b128 v[88:91], v32 offset:3072
	v_add_u32_e32 v32, s25, v239
	ds_read_b128 v[152:155], v32
	ds_read_b128 v[156:159], v32 offset:1024
	ds_read_b128 v[160:163], v32 offset:2048
	ds_read_b128 v[164:167], v32 offset:3072
	s_add_i32 m0, s56, 0xc000
	ds_read_b128 v[168:171], v251
	ds_read_b128 v[172:175], v251 offset:1024
	ds_read_b128 v[176:179], v251 offset:2048
	ds_read_b128 v[200:203], v251 offset:3072
	ds_read_b128 v[204:207], v251 offset:4096
	ds_read_b128 v[208:211], v251 offset:5120
	ds_read_b128 v[212:215], v251 offset:6144
	ds_read_b128 v[216:219], v251 offset:7168
	global_load_lds_dwordx4 v196, s[28:29]
	s_add_i32 m0, s56, 0xe000
	s_nop 0
	global_load_lds_dwordx4 v198, s[28:29]
	s_waitcnt vmcnt(8)
	s_waitcnt lgkmcnt(0)
	s_barrier
	s_setprio 1
	s_waitcnt lgkmcnt(0)
	v_mfma_f32_16x16x32_bf16 v[84:87], v[72:75], v[168:171], v[84:87]
	v_mfma_f32_16x16x32_bf16 v[84:87], v[76:79], v[172:175], v[84:87]
	v_mfma_f32_16x16x32_bf16 v[148:151], v[88:91], v[172:175], v[148:151]
	v_mfma_f32_16x16x32_bf16 v[148:151], v[80:83], v[168:171], v[148:151]
	v_mfma_f32_16x16x32_bf16 v[132:135], v[80:83], v[176:179], v[132:135]
	v_mfma_f32_16x16x32_bf16 v[132:135], v[88:91], v[200:203], v[132:135]
	v_mfma_f32_16x16x32_bf16 v[136:139], v[76:79], v[200:203], v[136:139]
	v_mfma_f32_16x16x32_bf16 v[136:139], v[72:75], v[176:179], v[136:139]
	v_mfma_f32_16x16x32_bf16 v[120:123], v[72:75], v[204:207], v[120:123]
	v_mfma_f32_16x16x32_bf16 v[120:123], v[76:79], v[208:211], v[120:123]
	v_mfma_f32_16x16x32_bf16 v[116:119], v[88:91], v[208:211], v[116:119]
	v_mfma_f32_16x16x32_bf16 v[116:119], v[80:83], v[204:207], v[116:119]
	v_mfma_f32_16x16x32_bf16 v[100:103], v[80:83], v[212:215], v[100:103]
	v_mfma_f32_16x16x32_bf16 v[100:103], v[88:91], v[216:219], v[100:103]
	v_mfma_f32_16x16x32_bf16 v[104:107], v[76:79], v[216:219], v[104:107]
	v_mfma_f32_16x16x32_bf16 v[104:107], v[72:75], v[212:215], v[104:107]
	s_setprio 0
	s_setprio 1
	v_mfma_f32_16x16x32_bf16 v[144:147], v[152:155], v[168:171], v[144:147]
	v_mfma_f32_16x16x32_bf16 v[144:147], v[156:159], v[172:175], v[144:147]
	v_mfma_f32_16x16x32_bf16 v[140:143], v[164:167], v[172:175], v[140:143]
	v_mfma_f32_16x16x32_bf16 v[140:143], v[160:163], v[168:171], v[140:143]
	v_mfma_f32_16x16x32_bf16 v[124:127], v[160:163], v[176:179], v[124:127]
	v_mfma_f32_16x16x32_bf16 v[124:127], v[164:167], v[200:203], v[124:127]
	v_mfma_f32_16x16x32_bf16 v[128:131], v[156:159], v[200:203], v[128:131]
	v_mfma_f32_16x16x32_bf16 v[128:131], v[152:155], v[176:179], v[128:131]
	v_mfma_f32_16x16x32_bf16 v[112:115], v[152:155], v[204:207], v[112:115]
	v_mfma_f32_16x16x32_bf16 v[112:115], v[156:159], v[208:211], v[112:115]
	v_mfma_f32_16x16x32_bf16 v[108:111], v[164:167], v[208:211], v[108:111]
	v_mfma_f32_16x16x32_bf16 v[108:111], v[160:163], v[204:207], v[108:111]
	v_mfma_f32_16x16x32_bf16 v[92:95], v[160:163], v[212:215], v[92:95]
	v_mfma_f32_16x16x32_bf16 v[92:95], v[164:167], v[216:219], v[92:95]
	v_mfma_f32_16x16x32_bf16 v[96:99], v[156:159], v[216:219], v[96:99]
	v_mfma_f32_16x16x32_bf16 v[96:99], v[152:155], v[212:215], v[96:99]
	s_setprio 0
	s_barrier
	s_add_i32 s23, s23, s3
	v_lshl_add_u64 v[186:187], s[38:39], 0, v[30:31]
	s_mov_b32 m0, s23
	ds_read_b128 v[168:171], v251 offset:16384
	ds_read_b128 v[172:175], v251 offset:17408
	ds_read_b128 v[176:179], v251 offset:18432
	ds_read_b128 v[200:203], v251 offset:19456
	ds_read_b128 v[204:207], v251 offset:20480
	ds_read_b128 v[208:211], v251 offset:21504
	ds_read_b128 v[212:215], v251 offset:22528
	ds_read_b128 v[216:219], v251 offset:23552
	global_load_lds_dwordx4 v[186:187], off
	s_add_i32 m0, s23, 0x2000
	s_add_u32 s28, s38, 0x80000
	v_lshl_add_u64 v[188:189], s[38:39], 0, v[180:181]
	s_addc_u32 s29, s39, 0
	s_add_i32 s23, s25, s3
	global_load_lds_dwordx4 v[188:189], off
	s_mov_b32 m0, s23
	v_lshl_add_u64 v[190:191], s[92:93], 0, v[30:31]
	global_load_lds_dwordx4 v30, s[28:29]
	v_lshl_add_u64 v[34:35], s[28:29], 0, v[180:181]
	s_add_i32 m0, s23, 0x2000
	v_lshl_add_u64 v[220:221], s[92:93], 0, v[180:181]
	global_load_lds_dwordx4 v[34:35], off
	s_mov_b32 m0, s56
	s_nop 0
	global_load_lds_dwordx4 v[190:191], off
	s_mov_b32 m0, s41
	s_nop 0
	global_load_lds_dwordx4 v[220:221], off
	s_waitcnt vmcnt(8)
	s_waitcnt lgkmcnt(0)
	s_barrier
; #define PG8_STAGE(bufoff, gbase, voff) do { _Pragma("unroll") for (int _i = 0; _i < 2; ++_i) \
;         __builtin_amdgcn_global_load_lds((const unsigned*)((const char*)(gbase) + (voff)[_i]), (PG8_LAS unsigned*)(lds + (bufoff) + ldsw + _i * 8192), 16, 0, 0); } while (0)
; #define PG8_LDA(dst, b, h) do { _Pragma("unroll") for (int m = 0; m < 4; ++m) _Pragma("unroll") for (int k = 0; k < 2; ++k) dst[m][k] = *(const PG8_LAS bf16x8*)(lds + PG8_SA(b, h) + aoff + m * 2048 + k * 1024); } while (0)
; #define PG8_LDB(dst, b, h) do { _Pragma("unroll") for (int n = 0; n < 2; ++n) _Pragma("unroll") for (int k = 0; k < 2; ++k) dst[n][k] = *(const PG8_LAS bf16x8*)(lds + PG8_SB(b, h) + boff + n * 2048 + k * 1024); } while (0)
; #define PG8_MMA(ai, bj, At, Bt) do { __builtin_amdgcn_s_setprio(1); _Pragma("unroll") for (int m = 0; m < 4; ++m) _Pragma("unroll") for (int n = 0; n < 2; ++n) _Pragma("unroll") for (int k = 0; k < 2; ++k) \
;         acc[ai][bj][m][n] = __builtin_amdgcn_mfma_f32_16x16x32_bf16(Bt[n][k], At[m][k], acc[ai][bj][m][n], 0, 0, 0); __builtin_amdgcn_s_setprio(0); } while (0)
; #define PG8_WAIT_V(n) asm volatile("s_waitcnt vmcnt(" #n ")" ::: "memory")
; #define PG8_WAIT_L(n) asm volatile("s_waitcnt lgkmcnt(" #n ")" ::: "memory")
; #define PG8_BAR __builtin_amdgcn_s_barrier()
; #define PG8_SCHED __builtin_amdgcn_sched_barrier(0)
;     ...
;             PG8_WAIT_V(8); PG8_WAIT_L(0); PG8_BAR; PG8_MMA(1, 0, At, B0); PG8_MMA(1, 1, At, B1); PG8_BAR; PG8_SCHED;
;             PG8_LDB(B0, 1, 0); PG8_LDB(B1, 1, 1); PG8_SCHED; PG8_LDA(At, 1, 0); PG8_STAGE(PG8_SA(0, 1), a2 + hstepA, voffA);
;             PG8_WAIT_V(8); PG8_WAIT_L(0); PG8_BAR; PG8_MMA(0, 0, At, B0); PG8_MMA(0, 1, At, B1); PG8_BAR; PG8_SCHED;
	s_setprio 1
	s_waitcnt lgkmcnt(0)
	v_mfma_f32_16x16x32_bf16 v[68:71], v[72:75], v[168:171], v[68:71]
	v_mfma_f32_16x16x32_bf16 v[68:71], v[76:79], v[172:175], v[68:71]
	v_mfma_f32_16x16x32_bf16 v[64:67], v[88:91], v[172:175], v[64:67]
	v_mfma_f32_16x16x32_bf16 v[64:67], v[80:83], v[168:171], v[64:67]
	v_mfma_f32_16x16x32_bf16 v[48:51], v[80:83], v[176:179], v[48:51]
	v_mfma_f32_16x16x32_bf16 v[48:51], v[88:91], v[200:203], v[48:51]
	v_mfma_f32_16x16x32_bf16 v[52:55], v[76:79], v[200:203], v[52:55]
	v_mfma_f32_16x16x32_bf16 v[52:55], v[72:75], v[176:179], v[52:55]
	v_mfma_f32_16x16x32_bf16 v[34:37], v[72:75], v[204:207], v[36:39]
	v_mfma_f32_16x16x32_bf16 v[34:37], v[76:79], v[208:211], v[34:37]
	v_mfma_f32_16x16x32_bf16 v[26:29], v[88:91], v[208:211], v[26:29]
	v_mfma_f32_16x16x32_bf16 v[26:29], v[80:83], v[204:207], v[26:29]
	v_mfma_f32_16x16x32_bf16 v[10:13], v[80:83], v[212:215], v[10:13]
	v_mfma_f32_16x16x32_bf16 v[10:13], v[88:91], v[216:219], v[10:13]
	v_mfma_f32_16x16x32_bf16 v[14:17], v[76:79], v[216:219], v[14:17]
	v_mfma_f32_16x16x32_bf16 v[14:17], v[72:75], v[212:215], v[14:17]
	s_setprio 0
	s_setprio 1
	v_mfma_f32_16x16x32_bf16 v[60:63], v[152:155], v[168:171], v[60:63]
	v_mfma_f32_16x16x32_bf16 v[60:63], v[156:159], v[172:175], v[60:63]
	v_mfma_f32_16x16x32_bf16 v[56:59], v[164:167], v[172:175], v[56:59]
	v_mfma_f32_16x16x32_bf16 v[56:59], v[160:163], v[168:171], v[56:59]
	v_mfma_f32_16x16x32_bf16 v[38:41], v[160:163], v[176:179], v[40:43]
	v_mfma_f32_16x16x32_bf16 v[40:43], v[164:167], v[200:203], v[38:41]
	v_mfma_f32_16x16x32_bf16 v[44:47], v[156:159], v[200:203], v[44:47]
	v_mfma_f32_16x16x32_bf16 v[44:47], v[152:155], v[176:179], v[44:47]
	v_mfma_f32_16x16x32_bf16 v[22:25], v[152:155], v[204:207], v[22:25]
	v_mfma_f32_16x16x32_bf16 v[22:25], v[156:159], v[208:211], v[22:25]
	v_mfma_f32_16x16x32_bf16 v[18:21], v[164:167], v[208:211], v[18:21]
	v_mfma_f32_16x16x32_bf16 v[18:21], v[160:163], v[204:207], v[18:21]
	v_mfma_f32_16x16x32_bf16 v[2:5], v[160:163], v[212:215], v[2:5]
	v_mfma_f32_16x16x32_bf16 v[2:5], v[164:167], v[216:219], v[2:5]
	v_mfma_f32_16x16x32_bf16 v[6:9], v[156:159], v[216:219], v[6:9]
	v_mfma_f32_16x16x32_bf16 v[6:9], v[152:155], v[212:215], v[6:9]
	s_setprio 0
	s_barrier
	s_add_i32 s23, 0, 0x18000
	v_add_u32_e32 v32, s23, v239
	s_add_i32 s25, 0, 0x1c000
	ds_read_b128 v[72:75], v32
	ds_read_b128 v[76:79], v32 offset:1024
	ds_read_b128 v[80:83], v32 offset:2048
	ds_read_b128 v[88:91], v32 offset:3072
	v_add_u32_e32 v32, s25, v239
	ds_read_b128 v[152:155], v32
	ds_read_b128 v[156:159], v32 offset:1024
	ds_read_b128 v[160:163], v32 offset:2048
	ds_read_b128 v[164:167], v32 offset:3072
	s_add_u32 s28, s92, 0x80000
	s_addc_u32 s29, s93, 0
	s_mov_b32 m0, s74
	ds_read_b128 v[168:171], v251 offset:32768
	ds_read_b128 v[172:175], v251 offset:33792
	ds_read_b128 v[176:179], v251 offset:34816
	ds_read_b128 v[200:203], v251 offset:35840
	ds_read_b128 v[204:207], v251 offset:36864
	ds_read_b128 v[208:211], v251 offset:37888
	ds_read_b128 v[212:215], v251 offset:38912
	ds_read_b128 v[216:219], v251 offset:39936
	global_load_lds_dwordx4 v30, s[28:29]
	s_mov_b32 m0, s96
	s_nop 0
	global_load_lds_dwordx4 v180, s[28:29]
	s_waitcnt vmcnt(8)
	s_waitcnt lgkmcnt(0)
	s_barrier
	s_setprio 1
	s_waitcnt lgkmcnt(0)
	v_mfma_f32_16x16x32_bf16 v[84:87], v[72:75], v[168:171], v[84:87]
	v_mfma_f32_16x16x32_bf16 v[84:87], v[76:79], v[172:175], v[84:87]
	v_mfma_f32_16x16x32_bf16 v[148:151], v[88:91], v[172:175], v[148:151]
	v_mfma_f32_16x16x32_bf16 v[148:151], v[80:83], v[168:171], v[148:151]
	v_mfma_f32_16x16x32_bf16 v[132:135], v[80:83], v[176:179], v[132:135]
	v_mfma_f32_16x16x32_bf16 v[132:135], v[88:91], v[200:203], v[132:135]
	v_mfma_f32_16x16x32_bf16 v[136:139], v[76:79], v[200:203], v[136:139]
	v_mfma_f32_16x16x32_bf16 v[136:139], v[72:75], v[176:179], v[136:139]
	v_mfma_f32_16x16x32_bf16 v[120:123], v[72:75], v[204:207], v[120:123]
	v_mfma_f32_16x16x32_bf16 v[120:123], v[76:79], v[208:211], v[120:123]
	v_mfma_f32_16x16x32_bf16 v[116:119], v[88:91], v[208:211], v[116:119]
	v_mfma_f32_16x16x32_bf16 v[116:119], v[80:83], v[204:207], v[116:119]
	v_mfma_f32_16x16x32_bf16 v[100:103], v[80:83], v[212:215], v[100:103]
	v_mfma_f32_16x16x32_bf16 v[100:103], v[88:91], v[216:219], v[100:103]
	v_mfma_f32_16x16x32_bf16 v[104:107], v[76:79], v[216:219], v[104:107]
	v_mfma_f32_16x16x32_bf16 v[104:107], v[72:75], v[212:215], v[104:107]
	s_setprio 0
	s_setprio 1
	v_mfma_f32_16x16x32_bf16 v[144:147], v[152:155], v[168:171], v[144:147]
	v_mfma_f32_16x16x32_bf16 v[144:147], v[156:159], v[172:175], v[144:147]
	v_mfma_f32_16x16x32_bf16 v[140:143], v[164:167], v[172:175], v[140:143]
	v_mfma_f32_16x16x32_bf16 v[140:143], v[160:163], v[168:171], v[140:143]
	v_mfma_f32_16x16x32_bf16 v[124:127], v[160:163], v[176:179], v[124:127]
	v_mfma_f32_16x16x32_bf16 v[124:127], v[164:167], v[200:203], v[124:127]
	v_mfma_f32_16x16x32_bf16 v[128:131], v[156:159], v[200:203], v[128:131]
	v_mfma_f32_16x16x32_bf16 v[128:131], v[152:155], v[176:179], v[128:131]
	v_mfma_f32_16x16x32_bf16 v[112:115], v[152:155], v[204:207], v[112:115]
	v_mfma_f32_16x16x32_bf16 v[112:115], v[156:159], v[208:211], v[112:115]
	v_mfma_f32_16x16x32_bf16 v[108:111], v[164:167], v[208:211], v[108:111]
	v_mfma_f32_16x16x32_bf16 v[108:111], v[160:163], v[204:207], v[108:111]
	v_mfma_f32_16x16x32_bf16 v[92:95], v[160:163], v[212:215], v[92:95]
	v_mfma_f32_16x16x32_bf16 v[92:95], v[164:167], v[216:219], v[92:95]
	v_mfma_f32_16x16x32_bf16 v[96:99], v[156:159], v[216:219], v[96:99]
	v_mfma_f32_16x16x32_bf16 v[96:99], v[152:155], v[212:215], v[96:99]
	s_setprio 0
	s_barrier
; #define PG8_STAGE(bufoff, gbase, voff) do { _Pragma("unroll") for (int _i = 0; _i < 2; ++_i) \
;         __builtin_amdgcn_global_load_lds((const unsigned*)((const char*)(gbase) + (voff)[_i]), (PG8_LAS unsigned*)(lds + (bufoff) + ldsw + _i * 8192), 16, 0, 0); } while (0)
; #define PG8_LDA(dst, b, h) do { _Pragma("unroll") for (int m = 0; m < 4; ++m) _Pragma("unroll") for (int k = 0; k < 2; ++k) dst[m][k] = *(const PG8_LAS bf16x8*)(lds + PG8_SA(b, h) + aoff + m * 2048 + k * 1024); } while (0)
; #define PG8_MMA(ai, bj, At, Bt) do { __builtin_amdgcn_s_setprio(1); _Pragma("unroll") for (int m = 0; m < 4; ++m) _Pragma("unroll") for (int n = 0; n < 2; ++n) _Pragma("unroll") for (int k = 0; k < 2; ++k) \
;         acc[ai][bj][m][n] = __builtin_amdgcn_mfma_f32_16x16x32_bf16(Bt[n][k], At[m][k], acc[ai][bj][m][n], 0, 0, 0); __builtin_amdgcn_s_setprio(0); } while (0)
; #define PG8_WAIT_V(n) asm volatile("s_waitcnt vmcnt(" #n ")" ::: "memory")
; #define PG8_WAIT_L(n) asm volatile("s_waitcnt lgkmcnt(" #n ")" ::: "memory")
; #define PG8_BAR __builtin_amdgcn_s_barrier()
; #define PG8_SCHED __builtin_amdgcn_sched_barrier(0)
;     ...
;         for (int t = 0; t < nt; t += 2) {
;             const bool last = (t == nt - 2);
;             const char* a1 = cA + (size_t)(t + 1) * kstep;
;             const char* a2 = last ? nA : cA + (size_t)(t + 2) * kstep; const char* b2 = last ? nB : cB + (size_t)(t + 2) * kstep;
;     ...
;             PG8_LDA(At, 1, 1); PG8_STAGE(PG8_SB(1, 0), b3, voffB); PG8_STAGE(PG8_SB(1, 1), b3 + hstep, voffB); PG8_STAGE(PG8_SA(1, 0), a3, voffA);
;             PG8_WAIT_V(8); PG8_WAIT_L(0); PG8_BAR; PG8_MMA(1, 0, At, B0); PG8_MMA(1, 1, At, B1); PG8_BAR; PG8_SCHED;
	s_add_i32 s23, s23, s3
	v_lshl_add_u64 v[38:39], v[186:187], 0, s[64:65]
	s_mov_b32 m0, s23
	ds_read_b128 v[168:171], v251 offset:49152
	ds_read_b128 v[172:175], v251 offset:50176
	ds_read_b128 v[176:179], v251 offset:51200
	ds_read_b128 v[200:203], v251 offset:52224
	ds_read_b128 v[204:207], v251 offset:53248
	ds_read_b128 v[208:211], v251 offset:54272
	ds_read_b128 v[212:215], v251 offset:55296
	ds_read_b128 v[216:219], v251 offset:56320
	global_load_lds_dwordx4 v[38:39], off
	s_add_i32 m0, s23, 0x2000
	s_add_u32 s28, s38, 0x80080
	v_lshl_add_u64 v[38:39], v[188:189], 0, s[64:65]
	s_addc_u32 s29, s39, 0
	s_add_i32 s23, s25, s3
	global_load_lds_dwordx4 v[38:39], off
	s_mov_b32 m0, s23
	s_nop 0
	global_load_lds_dwordx4 v30, s[28:29]
	s_add_i32 m0, s23, 0x2000
	s_nop 0
	global_load_lds_dwordx4 v180, s[28:29]
	v_lshl_add_u64 v[38:39], v[190:191], 0, s[64:65]
	s_mov_b32 m0, s53
	s_nop 0
	global_load_lds_dwordx4 v[38:39], off
	v_lshl_add_u64 v[38:39], v[220:221], 0, s[64:65]
	s_mov_b32 m0, s4
	s_nop 0
	global_load_lds_dwordx4 v[38:39], off
	s_waitcnt vmcnt(8)
	s_waitcnt lgkmcnt(0)
	s_barrier
	s_setprio 1
	s_waitcnt lgkmcnt(0)
	v_mfma_f32_16x16x32_bf16 v[68:71], v[72:75], v[168:171], v[68:71]
	v_mfma_f32_16x16x32_bf16 v[68:71], v[76:79], v[172:175], v[68:71]
	v_mfma_f32_16x16x32_bf16 v[64:67], v[88:91], v[172:175], v[64:67]
	v_mfma_f32_16x16x32_bf16 v[64:67], v[80:83], v[168:171], v[64:67]
	v_mfma_f32_16x16x32_bf16 v[48:51], v[80:83], v[176:179], v[48:51]
	v_mfma_f32_16x16x32_bf16 v[48:51], v[88:91], v[200:203], v[48:51]
	v_mfma_f32_16x16x32_bf16 v[52:55], v[76:79], v[200:203], v[52:55]
	v_mfma_f32_16x16x32_bf16 v[52:55], v[72:75], v[176:179], v[52:55]
	v_mfma_f32_16x16x32_bf16 v[34:37], v[72:75], v[204:207], v[34:37]
	v_mfma_f32_16x16x32_bf16 v[36:39], v[76:79], v[208:211], v[34:37]
	v_mfma_f32_16x16x32_bf16 v[26:29], v[88:91], v[208:211], v[26:29]
	v_mfma_f32_16x16x32_bf16 v[26:29], v[80:83], v[204:207], v[26:29]
	v_mfma_f32_16x16x32_bf16 v[10:13], v[80:83], v[212:215], v[10:13]
	v_mfma_f32_16x16x32_bf16 v[10:13], v[88:91], v[216:219], v[10:13]
	v_mfma_f32_16x16x32_bf16 v[14:17], v[76:79], v[216:219], v[14:17]
	v_mfma_f32_16x16x32_bf16 v[14:17], v[72:75], v[212:215], v[14:17]
	s_setprio 0
	s_setprio 1
	v_mfma_f32_16x16x32_bf16 v[60:63], v[152:155], v[168:171], v[60:63]
	v_mfma_f32_16x16x32_bf16 v[60:63], v[156:159], v[172:175], v[60:63]
	v_mfma_f32_16x16x32_bf16 v[56:59], v[164:167], v[172:175], v[56:59]
	v_mfma_f32_16x16x32_bf16 v[56:59], v[160:163], v[168:171], v[56:59]
	v_mfma_f32_16x16x32_bf16 v[40:43], v[160:163], v[176:179], v[40:43]
	v_mfma_f32_16x16x32_bf16 v[40:43], v[164:167], v[200:203], v[40:43]
	v_mfma_f32_16x16x32_bf16 v[44:47], v[156:159], v[200:203], v[44:47]
	v_mfma_f32_16x16x32_bf16 v[44:47], v[152:155], v[176:179], v[44:47]
	v_mfma_f32_16x16x32_bf16 v[22:25], v[152:155], v[204:207], v[22:25]
	v_mfma_f32_16x16x32_bf16 v[22:25], v[156:159], v[208:211], v[22:25]
	v_mfma_f32_16x16x32_bf16 v[18:21], v[164:167], v[208:211], v[18:21]
	v_mfma_f32_16x16x32_bf16 v[18:21], v[160:163], v[204:207], v[18:21]
	v_mfma_f32_16x16x32_bf16 v[2:5], v[160:163], v[212:215], v[2:5]
	v_mfma_f32_16x16x32_bf16 v[2:5], v[164:167], v[216:219], v[2:5]
	v_mfma_f32_16x16x32_bf16 v[6:9], v[156:159], v[216:219], v[6:9]
	v_mfma_f32_16x16x32_bf16 v[6:9], v[152:155], v[212:215], v[6:9]
	s_setprio 0
	s_barrier
	s_add_i32 s23, s19, 2
	s_add_u32 s9, s9, 0x100
	s_addc_u32 s17, s17, 0
	s_cmp_ge_i32 s19, s40
	s_mov_b64 s[28:29], s[30:31]
	s_mov_b32 s19, s23
	s_cbranch_scc0 .LBB0_1064
	s_and_b64 vcc, exec, s[14:15]
	s_cbranch_vccz .LBB0_1067
	s_barrier

; #define PG8_STAGE(bufoff, gbase, voff) do { _Pragma("unroll") for (int _i = 0; _i < 2; ++_i) \
;         __builtin_amdgcn_global_load_lds((const unsigned*)((const char*)(gbase) + (voff)[_i]), (PG8_LAS unsigned*)(lds + (bufoff) + ldsw + _i * 8192), 16, 0, 0); } while (0)
; #define PG8_LDA(dst, b, h) do { _Pragma("unroll") for (int m = 0; m < 4; ++m) _Pragma("unroll") for (int k = 0; k < 2; ++k) dst[m][k] = *(const PG8_LAS bf16x8*)(lds + PG8_SA(b, h) + aoff + m * 2048 + k * 1024); } while (0)
; #define PG8_LDB(dst, b, h) do { _Pragma("unroll") for (int n = 0; n < 2; ++n) _Pragma("unroll") for (int k = 0; k < 2; ++k) dst[n][k] = *(const PG8_LAS bf16x8*)(lds + PG8_SB(b, h) + boff + n * 2048 + k * 1024); } while (0)
; #define PG8_MMA(ai, bj, At, Bt) do { __builtin_amdgcn_s_setprio(1); _Pragma("unroll") for (int m = 0; m < 4; ++m) _Pragma("unroll") for (int n = 0; n < 2; ++n) _Pragma("unroll") for (int k = 0; k < 2; ++k) \
;         acc[ai][bj][m][n] = __builtin_amdgcn_mfma_f32_16x16x32_bf16(Bt[n][k], At[m][k], acc[ai][bj][m][n], 0, 0, 0); __builtin_amdgcn_s_setprio(0); } while (0)
; #define PG8_WAIT_V(n) asm volatile("s_waitcnt vmcnt(" #n ")" ::: "memory")
; #define PG8_WAIT_L(n) asm volatile("s_waitcnt lgkmcnt(" #n ")" ::: "memory")
; #define PG8_BAR __builtin_amdgcn_s_barrier()
; #define PG8_SCHED __builtin_amdgcn_sched_barrier(0)
;     ...
;             if constexpr (SP2) {
;             PG8_LDB(B0, 0, 0); PG8_LDB(B1, 0, 1); PG8_SCHED; PG8_LDA(At, 0, 0); PG8_STAGE(PG8_SA(1, 1), a1 + hstepA, voffA);
;             PG8_WAIT_V(8); PG8_WAIT_L(0); PG8_BAR; PG8_MMA(0, 0, At, B0); PG8_MMA(0, 1, At, B1); PG8_BAR; PG8_SCHED;
;             PG8_LDA(At, 0, 1); PG8_STAGE(PG8_SB(0, 0), b2, voffB); PG8_STAGE(PG8_SB(0, 1), b2 + hstep, voffB); PG8_STAGE(PG8_SA(0, 0), a2, voffA);
;             PG8_WAIT_V(8); PG8_WAIT_L(0); PG8_BAR; PG8_MMA(1, 0, At, B0); PG8_MMA(1, 1, At, B1); PG8_BAR; PG8_SCHED;
.LBB0_1332:
	s_add_u32 s26, s24, 0xfff80080
	s_addc_u32 s27, s25, -1
	s_add_i32 s42, 0, 0x10000
	s_cmp_eq_u32 s79, 28
	s_cselect_b32 s29, s11, s27
	s_cselect_b32 s28, s48, s26
	s_cselect_b32 s27, s9, s78
	s_cselect_b32 s26, s33, s74
	s_add_i32 s46, 0, 0x14000
	v_add_u32_e32 v106, s42, v31
	v_add_u32_e32 v174, s46, v31
	ds_read_b128 v[94:97], v106
	ds_read_b128 v[98:101], v106 offset:1024
	ds_read_b128 v[102:105], v106 offset:2048
	ds_read_b128 v[106:109], v106 offset:3072
	ds_read_b128 v[160:163], v174
	ds_read_b128 v[164:167], v174 offset:1024
	ds_read_b128 v[170:173], v174 offset:2048
	ds_read_b128 v[174:177], v174 offset:3072
	s_add_i32 m0, s19, 0xc000
	ds_read_b128 v[178:181], v169
	ds_read_b128 v[186:189], v169 offset:1024
	ds_read_b128 v[196:199], v169 offset:2048
	ds_read_b128 v[200:203], v169 offset:3072
	ds_read_b128 v[204:207], v169 offset:4096
	ds_read_b128 v[208:211], v169 offset:5120
	ds_read_b128 v[212:215], v169 offset:6144
	ds_read_b128 v[216:219], v169 offset:7168
	global_load_lds_dwordx4 v156, s[24:25]
	s_add_i32 m0, s19, 0xe000
	s_nop 0
	global_load_lds_dwordx4 v158, s[24:25]
	s_waitcnt vmcnt(8)
	s_waitcnt lgkmcnt(0)
	s_barrier
	s_setprio 1
	s_waitcnt lgkmcnt(0)
	v_mfma_f32_16x16x32_bf16 v[146:149], v[94:97], v[178:181], v[146:149]
	v_mfma_f32_16x16x32_bf16 v[146:149], v[98:101], v[186:189], v[146:149]
	v_mfma_f32_16x16x32_bf16 v[142:145], v[106:109], v[186:189], v[142:145]
	v_mfma_f32_16x16x32_bf16 v[142:145], v[102:105], v[178:181], v[142:145]
	v_mfma_f32_16x16x32_bf16 v[126:129], v[102:105], v[196:199], v[126:129]
	v_mfma_f32_16x16x32_bf16 v[126:129], v[106:109], v[200:203], v[126:129]
	v_mfma_f32_16x16x32_bf16 v[130:133], v[98:101], v[200:203], v[130:133]
	v_mfma_f32_16x16x32_bf16 v[130:133], v[94:97], v[196:199], v[130:133]
	v_mfma_f32_16x16x32_bf16 v[114:117], v[94:97], v[204:207], v[114:117]
	v_mfma_f32_16x16x32_bf16 v[114:117], v[98:101], v[208:211], v[114:117]
	v_mfma_f32_16x16x32_bf16 v[110:113], v[106:109], v[208:211], v[110:113]
	v_mfma_f32_16x16x32_bf16 v[110:113], v[102:105], v[204:207], v[110:113]
	v_mfma_f32_16x16x32_bf16 v[78:81], v[102:105], v[212:215], v[78:81]
	v_mfma_f32_16x16x32_bf16 v[78:81], v[106:109], v[216:219], v[78:81]
	v_mfma_f32_16x16x32_bf16 v[82:85], v[98:101], v[216:219], v[82:85]
	v_mfma_f32_16x16x32_bf16 v[82:85], v[94:97], v[212:215], v[82:85]
	s_setprio 0
	s_setprio 1
	v_mfma_f32_16x16x32_bf16 v[138:141], v[160:163], v[178:181], v[138:141]
	v_mfma_f32_16x16x32_bf16 v[138:141], v[164:167], v[186:189], v[138:141]
	v_mfma_f32_16x16x32_bf16 v[134:137], v[174:177], v[186:189], v[134:137]
	v_mfma_f32_16x16x32_bf16 v[134:137], v[170:173], v[178:181], v[134:137]
	v_mfma_f32_16x16x32_bf16 v[118:121], v[170:173], v[196:199], v[118:121]
	v_mfma_f32_16x16x32_bf16 v[118:121], v[174:177], v[200:203], v[118:121]
	v_mfma_f32_16x16x32_bf16 v[122:125], v[164:167], v[200:203], v[122:125]
	v_mfma_f32_16x16x32_bf16 v[122:125], v[160:163], v[196:199], v[122:125]
	v_mfma_f32_16x16x32_bf16 v[90:93], v[160:163], v[204:207], v[90:93]
	v_mfma_f32_16x16x32_bf16 v[90:93], v[164:167], v[208:211], v[90:93]
	v_mfma_f32_16x16x32_bf16 v[86:89], v[174:177], v[208:211], v[86:89]
	v_mfma_f32_16x16x32_bf16 v[86:89], v[170:173], v[204:207], v[86:89]
	v_mfma_f32_16x16x32_bf16 v[70:73], v[170:173], v[212:215], v[70:73]
	v_mfma_f32_16x16x32_bf16 v[70:73], v[174:177], v[216:219], v[70:73]
	v_mfma_f32_16x16x32_bf16 v[74:77], v[164:167], v[216:219], v[74:77]
	v_mfma_f32_16x16x32_bf16 v[74:77], v[160:163], v[212:215], v[74:77]
	s_setprio 0
	s_barrier
	s_add_i32 s42, s42, s30
	v_lshl_add_u64 v[182:183], s[26:27], 0, v[32:33]
	s_mov_b32 m0, s42
	ds_read_b128 v[178:181], v169 offset:16384
	ds_read_b128 v[186:189], v169 offset:17408
	ds_read_b128 v[196:199], v169 offset:18432
	ds_read_b128 v[200:203], v169 offset:19456
	ds_read_b128 v[204:207], v169 offset:20480
	ds_read_b128 v[208:211], v169 offset:21504
	ds_read_b128 v[212:215], v169 offset:22528
	ds_read_b128 v[216:219], v169 offset:23552
	global_load_lds_dwordx4 v[182:183], off
	s_add_i32 m0, s42, 0x2000
	s_add_u32 s42, s26, 0x80000
	v_lshl_add_u64 v[190:191], s[26:27], 0, v[154:155]
	s_addc_u32 s43, s27, 0
	s_add_i32 s46, s46, s30
	global_load_lds_dwordx4 v[190:191], off
	s_mov_b32 m0, s46
	v_lshl_add_u64 v[222:223], s[28:29], 0, v[152:153]
	global_load_lds_dwordx4 v32, s[42:43]
	s_add_i32 m0, s46, 0x2000
	s_nop 0
	global_load_lds_dwordx4 v154, s[42:43]
	v_lshl_add_u64 v[220:221], s[28:29], 0, v[150:151]
	s_mov_b32 m0, s19
	s_nop 0
	global_load_lds_dwordx4 v[220:221], off
	s_mov_b32 m0, s23
	s_nop 0
	global_load_lds_dwordx4 v[222:223], off
	s_waitcnt vmcnt(8)
	s_waitcnt lgkmcnt(0)
	s_barrier
; #define PG8_STAGE(bufoff, gbase, voff) do { _Pragma("unroll") for (int _i = 0; _i < 2; ++_i) \
;         __builtin_amdgcn_global_load_lds((const unsigned*)((const char*)(gbase) + (voff)[_i]), (PG8_LAS unsigned*)(lds + (bufoff) + ldsw + _i * 8192), 16, 0, 0); } while (0)
; #define PG8_LDA(dst, b, h) do { _Pragma("unroll") for (int m = 0; m < 4; ++m) _Pragma("unroll") for (int k = 0; k < 2; ++k) dst[m][k] = *(const PG8_LAS bf16x8*)(lds + PG8_SA(b, h) + aoff + m * 2048 + k * 1024); } while (0)
; #define PG8_LDB(dst, b, h) do { _Pragma("unroll") for (int n = 0; n < 2; ++n) _Pragma("unroll") for (int k = 0; k < 2; ++k) dst[n][k] = *(const PG8_LAS bf16x8*)(lds + PG8_SB(b, h) + boff + n * 2048 + k * 1024); } while (0)
; #define PG8_MMA(ai, bj, At, Bt) do { __builtin_amdgcn_s_setprio(1); _Pragma("unroll") for (int m = 0; m < 4; ++m) _Pragma("unroll") for (int n = 0; n < 2; ++n) _Pragma("unroll") for (int k = 0; k < 2; ++k) \
;         acc[ai][bj][m][n] = __builtin_amdgcn_mfma_f32_16x16x32_bf16(Bt[n][k], At[m][k], acc[ai][bj][m][n], 0, 0, 0); __builtin_amdgcn_s_setprio(0); } while (0)
; #define PG8_WAIT_V(n) asm volatile("s_waitcnt vmcnt(" #n ")" ::: "memory")
; #define PG8_WAIT_L(n) asm volatile("s_waitcnt lgkmcnt(" #n ")" ::: "memory")
; #define PG8_BAR __builtin_amdgcn_s_barrier()
; #define PG8_SCHED __builtin_amdgcn_sched_barrier(0)
;     ...
;             PG8_WAIT_V(8); PG8_WAIT_L(0); PG8_BAR; PG8_MMA(1, 0, At, B0); PG8_MMA(1, 1, At, B1); PG8_BAR; PG8_SCHED;
;             PG8_LDB(B0, 1, 0); PG8_LDB(B1, 1, 1); PG8_SCHED; PG8_LDA(At, 1, 0); PG8_STAGE(PG8_SA(0, 1), a2 + hstepA, voffA);
;             PG8_WAIT_V(8); PG8_WAIT_L(0); PG8_BAR; PG8_MMA(0, 0, At, B0); PG8_MMA(0, 1, At, B1); PG8_BAR; PG8_SCHED;
	s_setprio 1
	s_waitcnt lgkmcnt(0)
	v_mfma_f32_16x16x32_bf16 v[66:69], v[94:97], v[178:181], v[66:69]
	v_mfma_f32_16x16x32_bf16 v[66:69], v[98:101], v[186:189], v[66:69]
	v_mfma_f32_16x16x32_bf16 v[62:65], v[106:109], v[186:189], v[62:65]
	v_mfma_f32_16x16x32_bf16 v[62:65], v[102:105], v[178:181], v[62:65]
	v_mfma_f32_16x16x32_bf16 v[46:49], v[102:105], v[196:199], v[46:49]
	v_mfma_f32_16x16x32_bf16 v[46:49], v[106:109], v[200:203], v[46:49]
	v_mfma_f32_16x16x32_bf16 v[50:53], v[98:101], v[200:203], v[50:53]
	v_mfma_f32_16x16x32_bf16 v[50:53], v[94:97], v[196:199], v[50:53]
	v_mfma_f32_16x16x32_bf16 v[34:37], v[94:97], v[204:207], v[34:37]
	v_mfma_f32_16x16x32_bf16 v[34:37], v[98:101], v[208:211], v[34:37]
	v_mfma_f32_16x16x32_bf16 v[26:29], v[106:109], v[208:211], v[26:29]
	v_mfma_f32_16x16x32_bf16 v[26:29], v[102:105], v[204:207], v[26:29]
	v_mfma_f32_16x16x32_bf16 v[10:13], v[102:105], v[212:215], v[10:13]
	v_mfma_f32_16x16x32_bf16 v[10:13], v[106:109], v[216:219], v[10:13]
	v_mfma_f32_16x16x32_bf16 v[14:17], v[98:101], v[216:219], v[14:17]
	v_mfma_f32_16x16x32_bf16 v[14:17], v[94:97], v[212:215], v[14:17]
	s_setprio 0
	s_setprio 1
	v_mfma_f32_16x16x32_bf16 v[58:61], v[160:163], v[178:181], v[58:61]
	v_mfma_f32_16x16x32_bf16 v[58:61], v[164:167], v[186:189], v[58:61]
	v_mfma_f32_16x16x32_bf16 v[54:57], v[174:177], v[186:189], v[54:57]
	v_mfma_f32_16x16x32_bf16 v[54:57], v[170:173], v[178:181], v[54:57]
	v_mfma_f32_16x16x32_bf16 v[38:41], v[170:173], v[196:199], v[38:41]
	v_mfma_f32_16x16x32_bf16 v[38:41], v[174:177], v[200:203], v[38:41]
	v_mfma_f32_16x16x32_bf16 v[42:45], v[164:167], v[200:203], v[42:45]
	v_mfma_f32_16x16x32_bf16 v[42:45], v[160:163], v[196:199], v[42:45]
	v_mfma_f32_16x16x32_bf16 v[22:25], v[160:163], v[204:207], v[22:25]
	v_mfma_f32_16x16x32_bf16 v[22:25], v[164:167], v[208:211], v[22:25]
	v_mfma_f32_16x16x32_bf16 v[18:21], v[174:177], v[208:211], v[18:21]
	v_mfma_f32_16x16x32_bf16 v[18:21], v[170:173], v[204:207], v[18:21]
	v_mfma_f32_16x16x32_bf16 v[2:5], v[170:173], v[212:215], v[2:5]
	v_mfma_f32_16x16x32_bf16 v[2:5], v[174:177], v[216:219], v[2:5]
	v_mfma_f32_16x16x32_bf16 v[6:9], v[164:167], v[216:219], v[6:9]
	v_mfma_f32_16x16x32_bf16 v[6:9], v[160:163], v[212:215], v[6:9]
	s_setprio 0
	s_barrier
	s_add_i32 s42, 0, 0x18000
	s_add_i32 s43, 0, 0x1c000
	v_add_u32_e32 v106, s42, v31
	v_add_u32_e32 v174, s43, v31
	ds_read_b128 v[94:97], v106
	ds_read_b128 v[98:101], v106 offset:1024
	ds_read_b128 v[102:105], v106 offset:2048
	ds_read_b128 v[106:109], v106 offset:3072
	ds_read_b128 v[160:163], v174
	ds_read_b128 v[164:167], v174 offset:1024
	ds_read_b128 v[170:173], v174 offset:2048
	ds_read_b128 v[174:177], v174 offset:3072
	s_add_u32 s28, s28, 0x80000
	s_addc_u32 s29, s29, 0
	s_mov_b32 m0, s31
	ds_read_b128 v[178:181], v169 offset:32768
	ds_read_b128 v[186:189], v169 offset:33792
	ds_read_b128 v[196:199], v169 offset:34816
	ds_read_b128 v[200:203], v169 offset:35840
	ds_read_b128 v[204:207], v169 offset:36864
	ds_read_b128 v[208:211], v169 offset:37888
	ds_read_b128 v[212:215], v169 offset:38912
	ds_read_b128 v[216:219], v169 offset:39936
	global_load_lds_dwordx4 v150, s[28:29]
	v_lshl_add_u64 v[224:225], s[28:29], 0, v[152:153]
	s_mov_b32 m0, s38
	s_nop 0
	global_load_lds_dwordx4 v[224:225], off
	s_waitcnt vmcnt(8)
	s_waitcnt lgkmcnt(0)
	s_barrier
	s_setprio 1
	s_waitcnt lgkmcnt(0)
	v_mfma_f32_16x16x32_bf16 v[146:149], v[94:97], v[178:181], v[146:149]
	v_mfma_f32_16x16x32_bf16 v[146:149], v[98:101], v[186:189], v[146:149]
	v_mfma_f32_16x16x32_bf16 v[142:145], v[106:109], v[186:189], v[142:145]
	v_mfma_f32_16x16x32_bf16 v[142:145], v[102:105], v[178:181], v[142:145]
	v_mfma_f32_16x16x32_bf16 v[126:129], v[102:105], v[196:199], v[126:129]
	v_mfma_f32_16x16x32_bf16 v[126:129], v[106:109], v[200:203], v[126:129]
	v_mfma_f32_16x16x32_bf16 v[130:133], v[98:101], v[200:203], v[130:133]
	v_mfma_f32_16x16x32_bf16 v[130:133], v[94:97], v[196:199], v[130:133]
	v_mfma_f32_16x16x32_bf16 v[114:117], v[94:97], v[204:207], v[114:117]
	v_mfma_f32_16x16x32_bf16 v[114:117], v[98:101], v[208:211], v[114:117]
	v_mfma_f32_16x16x32_bf16 v[110:113], v[106:109], v[208:211], v[110:113]
	v_mfma_f32_16x16x32_bf16 v[110:113], v[102:105], v[204:207], v[110:113]
	v_mfma_f32_16x16x32_bf16 v[78:81], v[102:105], v[212:215], v[78:81]
	v_mfma_f32_16x16x32_bf16 v[78:81], v[106:109], v[216:219], v[78:81]
	v_mfma_f32_16x16x32_bf16 v[82:85], v[98:101], v[216:219], v[82:85]
	v_mfma_f32_16x16x32_bf16 v[82:85], v[94:97], v[212:215], v[82:85]
	s_setprio 0
	s_setprio 1
	v_mfma_f32_16x16x32_bf16 v[138:141], v[160:163], v[178:181], v[138:141]
	v_mfma_f32_16x16x32_bf16 v[138:141], v[164:167], v[186:189], v[138:141]
	v_mfma_f32_16x16x32_bf16 v[134:137], v[174:177], v[186:189], v[134:137]
	v_mfma_f32_16x16x32_bf16 v[134:137], v[170:173], v[178:181], v[134:137]
	v_mfma_f32_16x16x32_bf16 v[118:121], v[170:173], v[196:199], v[118:121]
	v_mfma_f32_16x16x32_bf16 v[118:121], v[174:177], v[200:203], v[118:121]
	v_mfma_f32_16x16x32_bf16 v[122:125], v[164:167], v[200:203], v[122:125]
	v_mfma_f32_16x16x32_bf16 v[122:125], v[160:163], v[196:199], v[122:125]
	v_mfma_f32_16x16x32_bf16 v[90:93], v[160:163], v[204:207], v[90:93]
	v_mfma_f32_16x16x32_bf16 v[90:93], v[164:167], v[208:211], v[90:93]
	v_mfma_f32_16x16x32_bf16 v[86:89], v[174:177], v[208:211], v[86:89]
	v_mfma_f32_16x16x32_bf16 v[86:89], v[170:173], v[204:207], v[86:89]
	v_mfma_f32_16x16x32_bf16 v[70:73], v[170:173], v[212:215], v[70:73]
	v_mfma_f32_16x16x32_bf16 v[70:73], v[174:177], v[216:219], v[70:73]
	v_mfma_f32_16x16x32_bf16 v[74:77], v[164:167], v[216:219], v[74:77]
	v_mfma_f32_16x16x32_bf16 v[74:77], v[160:163], v[212:215], v[74:77]
	s_setprio 0
	s_barrier
; #define PG8_STAGE(bufoff, gbase, voff) do { _Pragma("unroll") for (int _i = 0; _i < 2; ++_i) \
;         __builtin_amdgcn_global_load_lds((const unsigned*)((const char*)(gbase) + (voff)[_i]), (PG8_LAS unsigned*)(lds + (bufoff) + ldsw + _i * 8192), 16, 0, 0); } while (0)
; #define PG8_LDA(dst, b, h) do { _Pragma("unroll") for (int m = 0; m < 4; ++m) _Pragma("unroll") for (int k = 0; k < 2; ++k) dst[m][k] = *(const PG8_LAS bf16x8*)(lds + PG8_SA(b, h) + aoff + m * 2048 + k * 1024); } while (0)
; #define PG8_MMA(ai, bj, At, Bt) do { __builtin_amdgcn_s_setprio(1); _Pragma("unroll") for (int m = 0; m < 4; ++m) _Pragma("unroll") for (int n = 0; n < 2; ++n) _Pragma("unroll") for (int k = 0; k < 2; ++k) \
;         acc[ai][bj][m][n] = __builtin_amdgcn_mfma_f32_16x16x32_bf16(Bt[n][k], At[m][k], acc[ai][bj][m][n], 0, 0, 0); __builtin_amdgcn_s_setprio(0); } while (0)
; #define PG8_WAIT_V(n) asm volatile("s_waitcnt vmcnt(" #n ")" ::: "memory")
; #define PG8_WAIT_L(n) asm volatile("s_waitcnt lgkmcnt(" #n ")" ::: "memory")
; #define PG8_BAR __builtin_amdgcn_s_barrier()
; #define PG8_SCHED __builtin_amdgcn_sched_barrier(0)
;     ...
;         for (int t = 0; t < nt; t += 2) {
;             const bool last = (t == nt - 2);
;             const char* a1 = cA + (size_t)(t + 1) * kstep;
;             const char* a2 = last ? nA : cA + (size_t)(t + 2) * kstep; const char* b2 = last ? nB : cB + (size_t)(t + 2) * kstep;
;     ...
;             PG8_LDA(At, 1, 1); PG8_STAGE(PG8_SB(1, 0), b3, voffB); PG8_STAGE(PG8_SB(1, 1), b3 + hstep, voffB); PG8_STAGE(PG8_SA(1, 0), a3, voffA);
;             PG8_WAIT_V(8); PG8_WAIT_L(0); PG8_BAR; PG8_MMA(1, 0, At, B0); PG8_MMA(1, 1, At, B1); PG8_BAR; PG8_SCHED;
	s_add_i32 s28, s42, s30
	v_lshl_add_u64 v[182:183], v[182:183], 0, s[64:65]
	s_mov_b32 m0, s28
	ds_read_b128 v[178:181], v169 offset:49152
	ds_read_b128 v[186:189], v169 offset:50176
	ds_read_b128 v[196:199], v169 offset:51200
	ds_read_b128 v[200:203], v169 offset:52224
	ds_read_b128 v[204:207], v169 offset:53248
	ds_read_b128 v[208:211], v169 offset:54272
	ds_read_b128 v[212:215], v169 offset:55296
	ds_read_b128 v[216:219], v169 offset:56320
	global_load_lds_dwordx4 v[182:183], off
	s_add_i32 m0, s28, 0x2000
	s_add_u32 s26, s26, 0x80080
	v_lshl_add_u64 v[182:183], v[190:191], 0, s[64:65]
	s_addc_u32 s27, s27, 0
	s_add_i32 s28, s43, s30
	global_load_lds_dwordx4 v[182:183], off
	s_mov_b32 m0, s28
	s_nop 0
	global_load_lds_dwordx4 v32, s[26:27]
	s_add_i32 m0, s28, 0x2000
	s_nop 0
	global_load_lds_dwordx4 v154, s[26:27]
	v_lshl_add_u64 v[182:183], v[220:221], 0, s[64:65]
	s_mov_b32 m0, s41
	s_nop 0
	global_load_lds_dwordx4 v[182:183], off
	v_lshl_add_u64 v[182:183], v[222:223], 0, s[64:65]
	s_mov_b32 m0, s50
	s_nop 0
	global_load_lds_dwordx4 v[182:183], off
	s_waitcnt vmcnt(8)
	s_waitcnt lgkmcnt(0)
	s_barrier
	s_setprio 1
	s_waitcnt lgkmcnt(0)
	v_mfma_f32_16x16x32_bf16 v[66:69], v[94:97], v[178:181], v[66:69]
	v_mfma_f32_16x16x32_bf16 v[66:69], v[98:101], v[186:189], v[66:69]
	v_mfma_f32_16x16x32_bf16 v[62:65], v[106:109], v[186:189], v[62:65]
	v_mfma_f32_16x16x32_bf16 v[62:65], v[102:105], v[178:181], v[62:65]
	v_mfma_f32_16x16x32_bf16 v[46:49], v[102:105], v[196:199], v[46:49]
	v_mfma_f32_16x16x32_bf16 v[46:49], v[106:109], v[200:203], v[46:49]
	v_mfma_f32_16x16x32_bf16 v[50:53], v[98:101], v[200:203], v[50:53]
	v_mfma_f32_16x16x32_bf16 v[50:53], v[94:97], v[196:199], v[50:53]
	v_mfma_f32_16x16x32_bf16 v[34:37], v[94:97], v[204:207], v[34:37]
	v_mfma_f32_16x16x32_bf16 v[34:37], v[98:101], v[208:211], v[34:37]
	v_mfma_f32_16x16x32_bf16 v[26:29], v[106:109], v[208:211], v[26:29]
	v_mfma_f32_16x16x32_bf16 v[26:29], v[102:105], v[204:207], v[26:29]
	v_mfma_f32_16x16x32_bf16 v[10:13], v[102:105], v[212:215], v[10:13]
	v_mfma_f32_16x16x32_bf16 v[10:13], v[106:109], v[216:219], v[10:13]
	v_mfma_f32_16x16x32_bf16 v[14:17], v[98:101], v[216:219], v[14:17]
	v_mfma_f32_16x16x32_bf16 v[14:17], v[94:97], v[212:215], v[14:17]
	s_setprio 0
	s_setprio 1
	v_mfma_f32_16x16x32_bf16 v[58:61], v[160:163], v[178:181], v[58:61]
	v_mfma_f32_16x16x32_bf16 v[58:61], v[164:167], v[186:189], v[58:61]
	v_mfma_f32_16x16x32_bf16 v[54:57], v[174:177], v[186:189], v[54:57]
	v_mfma_f32_16x16x32_bf16 v[54:57], v[170:173], v[178:181], v[54:57]
	v_mfma_f32_16x16x32_bf16 v[38:41], v[170:173], v[196:199], v[38:41]
	v_mfma_f32_16x16x32_bf16 v[38:41], v[174:177], v[200:203], v[38:41]
	v_mfma_f32_16x16x32_bf16 v[42:45], v[164:167], v[200:203], v[42:45]
	v_mfma_f32_16x16x32_bf16 v[42:45], v[160:163], v[196:199], v[42:45]
	v_mfma_f32_16x16x32_bf16 v[22:25], v[160:163], v[204:207], v[22:25]
	v_mfma_f32_16x16x32_bf16 v[22:25], v[164:167], v[208:211], v[22:25]
	v_mfma_f32_16x16x32_bf16 v[18:21], v[174:177], v[208:211], v[18:21]
	v_mfma_f32_16x16x32_bf16 v[18:21], v[170:173], v[204:207], v[18:21]
	v_mfma_f32_16x16x32_bf16 v[2:5], v[170:173], v[212:215], v[2:5]
	v_mfma_f32_16x16x32_bf16 v[2:5], v[174:177], v[216:219], v[2:5]
	v_mfma_f32_16x16x32_bf16 v[6:9], v[164:167], v[216:219], v[6:9]
	v_mfma_f32_16x16x32_bf16 v[6:9], v[160:163], v[212:215], v[6:9]
	s_setprio 0
	s_barrier
	s_add_i32 s79, s79, 2
	s_add_u32 s24, s24, 0x100
	s_addc_u32 s25, s25, 0
	s_add_u32 s74, s74, 0x100
	s_addc_u32 s78, s78, 0
	s_cmp_gt_u32 s79, 29
	s_cbranch_scc0 .LBB0_1332
	s_and_b64 vcc, exec, s[6:7]
	s_cbranch_vccz .LBB0_1335
	s_barrier

; #define PG8_STAGE(bufoff, gbase, voff) do { _Pragma("unroll") for (int _i = 0; _i < 2; ++_i) \
;         __builtin_amdgcn_global_load_lds((const unsigned*)((const char*)(gbase) + (voff)[_i]), (PG8_LAS unsigned*)(lds + (bufoff) + ldsw + _i * 8192), 16, 0, 0); } while (0)
; #define PG8_LDA(dst, b, h) do { _Pragma("unroll") for (int m = 0; m < 4; ++m) _Pragma("unroll") for (int k = 0; k < 2; ++k) dst[m][k] = *(const PG8_LAS bf16x8*)(lds + PG8_SA(b, h) + aoff + m * 2048 + k * 1024); } while (0)
; #define PG8_LDB(dst, b, h) do { _Pragma("unroll") for (int n = 0; n < 2; ++n) _Pragma("unroll") for (int k = 0; k < 2; ++k) dst[n][k] = *(const PG8_LAS bf16x8*)(lds + PG8_SB(b, h) + boff + n * 2048 + k * 1024); } while (0)
; #define PG8_MMA(ai, bj, At, Bt) do { __builtin_amdgcn_s_setprio(1); _Pragma("unroll") for (int m = 0; m < 4; ++m) _Pragma("unroll") for (int n = 0; n < 2; ++n) _Pragma("unroll") for (int k = 0; k < 2; ++k) \
;         acc[ai][bj][m][n] = __builtin_amdgcn_mfma_f32_16x16x32_bf16(Bt[n][k], At[m][k], acc[ai][bj][m][n], 0, 0, 0); __builtin_amdgcn_s_setprio(0); } while (0)
; #define PG8_WAIT_V(n) asm volatile("s_waitcnt vmcnt(" #n ")" ::: "memory")
; #define PG8_WAIT_L(n) asm volatile("s_waitcnt lgkmcnt(" #n ")" ::: "memory")
; #define PG8_BAR __builtin_amdgcn_s_barrier()
; #define PG8_SCHED __builtin_amdgcn_sched_barrier(0)
;     ...
;             if constexpr (SP2) {
;             PG8_LDB(B0, 0, 0); PG8_LDB(B1, 0, 1); PG8_SCHED; PG8_LDA(At, 0, 0); PG8_STAGE(PG8_SA(1, 1), a1 + hstepA, voffA);
;             PG8_WAIT_V(8); PG8_WAIT_L(0); PG8_BAR; PG8_MMA(0, 0, At, B0); PG8_MMA(0, 1, At, B1); PG8_BAR; PG8_SCHED;
;             PG8_LDA(At, 0, 1); PG8_STAGE(PG8_SB(0, 0), b2, voffB); PG8_STAGE(PG8_SB(0, 1), b2 + hstep, voffB); PG8_STAGE(PG8_SA(0, 0), a2, voffA);
;             PG8_WAIT_V(8); PG8_WAIT_L(0); PG8_BAR; PG8_MMA(1, 0, At, B0); PG8_MMA(1, 1, At, B1); PG8_BAR; PG8_SCHED;
.LBB0_1454:
	s_add_u32 s30, s28, 0x100
	s_addc_u32 s31, s29, 0
	s_add_i32 s27, 0, 0x10000
	s_cmp_eq_u32 s40, s25
	s_cselect_b32 s93, s95, s31
	s_cselect_b32 s92, s94, s30
	v_add_u32_e32 v32, s27, v239
	s_cselect_b32 s39, s97, s23
	s_cselect_b32 s38, s96, s9
	s_add_i32 s33, 0, 0x14000
	ds_read_b128 v[72:75], v32
	ds_read_b128 v[76:79], v32 offset:1024
	ds_read_b128 v[80:83], v32 offset:2048
	ds_read_b128 v[88:91], v32 offset:3072
	v_add_u32_e32 v32, s33, v239
	ds_read_b128 v[152:155], v32
	ds_read_b128 v[156:159], v32 offset:1024
	ds_read_b128 v[160:163], v32 offset:2048
	ds_read_b128 v[164:167], v32 offset:3072
	s_add_i32 m0, s4, 0xc000
	ds_read_b128 v[168:171], v251
	ds_read_b128 v[172:175], v251 offset:1024
	ds_read_b128 v[176:179], v251 offset:2048
	ds_read_b128 v[186:189], v251 offset:3072
	ds_read_b128 v[200:203], v251 offset:4096
	ds_read_b128 v[204:207], v251 offset:5120
	ds_read_b128 v[208:211], v251 offset:6144
	ds_read_b128 v[212:215], v251 offset:7168
	global_load_lds_dwordx4 v196, s[28:29]
	s_add_i32 m0, s4, 0xe000
	s_nop 0
	global_load_lds_dwordx4 v198, s[28:29]
	s_waitcnt vmcnt(8)
	s_waitcnt lgkmcnt(0)
	s_barrier
	s_setprio 1
	s_waitcnt lgkmcnt(0)
	v_mfma_f32_16x16x32_bf16 v[84:87], v[72:75], v[168:171], v[84:87]
	v_mfma_f32_16x16x32_bf16 v[84:87], v[76:79], v[172:175], v[84:87]
	v_mfma_f32_16x16x32_bf16 v[148:151], v[88:91], v[172:175], v[148:151]
	v_mfma_f32_16x16x32_bf16 v[148:151], v[80:83], v[168:171], v[148:151]
	v_mfma_f32_16x16x32_bf16 v[132:135], v[80:83], v[176:179], v[132:135]
	v_mfma_f32_16x16x32_bf16 v[132:135], v[88:91], v[186:189], v[132:135]
	v_mfma_f32_16x16x32_bf16 v[136:139], v[76:79], v[186:189], v[136:139]
	v_mfma_f32_16x16x32_bf16 v[136:139], v[72:75], v[176:179], v[136:139]
	v_mfma_f32_16x16x32_bf16 v[120:123], v[72:75], v[200:203], v[120:123]
	v_mfma_f32_16x16x32_bf16 v[120:123], v[76:79], v[204:207], v[120:123]
	v_mfma_f32_16x16x32_bf16 v[116:119], v[88:91], v[204:207], v[116:119]
	v_mfma_f32_16x16x32_bf16 v[116:119], v[80:83], v[200:203], v[116:119]
	v_mfma_f32_16x16x32_bf16 v[100:103], v[80:83], v[208:211], v[100:103]
	v_mfma_f32_16x16x32_bf16 v[100:103], v[88:91], v[212:215], v[100:103]
	v_mfma_f32_16x16x32_bf16 v[104:107], v[76:79], v[212:215], v[104:107]
	v_mfma_f32_16x16x32_bf16 v[104:107], v[72:75], v[208:211], v[104:107]
	s_setprio 0
	s_setprio 1
	v_mfma_f32_16x16x32_bf16 v[144:147], v[152:155], v[168:171], v[144:147]
	v_mfma_f32_16x16x32_bf16 v[144:147], v[156:159], v[172:175], v[144:147]
	v_mfma_f32_16x16x32_bf16 v[140:143], v[164:167], v[172:175], v[140:143]
	v_mfma_f32_16x16x32_bf16 v[140:143], v[160:163], v[168:171], v[140:143]
	v_mfma_f32_16x16x32_bf16 v[124:127], v[160:163], v[176:179], v[124:127]
	v_mfma_f32_16x16x32_bf16 v[124:127], v[164:167], v[186:189], v[124:127]
	v_mfma_f32_16x16x32_bf16 v[128:131], v[156:159], v[186:189], v[128:131]
	v_mfma_f32_16x16x32_bf16 v[128:131], v[152:155], v[176:179], v[128:131]
	v_mfma_f32_16x16x32_bf16 v[112:115], v[152:155], v[200:203], v[112:115]
	v_mfma_f32_16x16x32_bf16 v[112:115], v[156:159], v[204:207], v[112:115]
	v_mfma_f32_16x16x32_bf16 v[108:111], v[164:167], v[204:207], v[108:111]
	v_mfma_f32_16x16x32_bf16 v[108:111], v[160:163], v[200:203], v[108:111]
	v_mfma_f32_16x16x32_bf16 v[92:95], v[160:163], v[208:211], v[92:95]
	v_mfma_f32_16x16x32_bf16 v[92:95], v[164:167], v[212:215], v[92:95]
	v_mfma_f32_16x16x32_bf16 v[96:99], v[156:159], v[212:215], v[96:99]
	v_mfma_f32_16x16x32_bf16 v[96:99], v[152:155], v[208:211], v[96:99]
	s_setprio 0
	s_barrier
	s_add_i32 s27, s27, s3
	v_lshl_add_u64 v[190:191], s[38:39], 0, v[30:31]
	s_mov_b32 m0, s27
	ds_read_b128 v[168:171], v251 offset:16384
	ds_read_b128 v[172:175], v251 offset:17408
	ds_read_b128 v[176:179], v251 offset:18432
	ds_read_b128 v[186:189], v251 offset:19456
	ds_read_b128 v[200:203], v251 offset:20480
	ds_read_b128 v[204:207], v251 offset:21504
	ds_read_b128 v[208:211], v251 offset:22528
	ds_read_b128 v[212:215], v251 offset:23552
	global_load_lds_dwordx4 v[190:191], off
	s_add_i32 m0, s27, 0x2000
	s_add_u32 s28, s38, 0x200000
	v_lshl_add_u64 v[216:217], s[38:39], 0, v[180:181]
	s_addc_u32 s29, s39, 0
	s_add_i32 s27, s33, s3
	global_load_lds_dwordx4 v[216:217], off
	s_mov_b32 m0, s27
	v_lshl_add_u64 v[218:219], s[92:93], 0, v[30:31]
	global_load_lds_dwordx4 v30, s[28:29]
	v_lshl_add_u64 v[34:35], s[28:29], 0, v[180:181]
	s_add_i32 m0, s27, 0x2000
	v_lshl_add_u64 v[220:221], s[92:93], 0, v[180:181]
	global_load_lds_dwordx4 v[34:35], off
	s_mov_b32 m0, s4
	s_nop 0
	global_load_lds_dwordx4 v[218:219], off
	s_mov_b32 m0, s5
	s_nop 0
	global_load_lds_dwordx4 v[220:221], off
	s_waitcnt vmcnt(8)
	s_waitcnt lgkmcnt(0)
	s_barrier
; #define PG8_STAGE(bufoff, gbase, voff) do { _Pragma("unroll") for (int _i = 0; _i < 2; ++_i) \
;         __builtin_amdgcn_global_load_lds((const unsigned*)((const char*)(gbase) + (voff)[_i]), (PG8_LAS unsigned*)(lds + (bufoff) + ldsw + _i * 8192), 16, 0, 0); } while (0)
; #define PG8_LDA(dst, b, h) do { _Pragma("unroll") for (int m = 0; m < 4; ++m) _Pragma("unroll") for (int k = 0; k < 2; ++k) dst[m][k] = *(const PG8_LAS bf16x8*)(lds + PG8_SA(b, h) + aoff + m * 2048 + k * 1024); } while (0)
; #define PG8_LDB(dst, b, h) do { _Pragma("unroll") for (int n = 0; n < 2; ++n) _Pragma("unroll") for (int k = 0; k < 2; ++k) dst[n][k] = *(const PG8_LAS bf16x8*)(lds + PG8_SB(b, h) + boff + n * 2048 + k * 1024); } while (0)
; #define PG8_MMA(ai, bj, At, Bt) do { __builtin_amdgcn_s_setprio(1); _Pragma("unroll") for (int m = 0; m < 4; ++m) _Pragma("unroll") for (int n = 0; n < 2; ++n) _Pragma("unroll") for (int k = 0; k < 2; ++k) \
;         acc[ai][bj][m][n] = __builtin_amdgcn_mfma_f32_16x16x32_bf16(Bt[n][k], At[m][k], acc[ai][bj][m][n], 0, 0, 0); __builtin_amdgcn_s_setprio(0); } while (0)
; #define PG8_WAIT_V(n) asm volatile("s_waitcnt vmcnt(" #n ")" ::: "memory")
; #define PG8_WAIT_L(n) asm volatile("s_waitcnt lgkmcnt(" #n ")" ::: "memory")
; #define PG8_BAR __builtin_amdgcn_s_barrier()
; #define PG8_SCHED __builtin_amdgcn_sched_barrier(0)
;     ...
;             PG8_WAIT_V(8); PG8_WAIT_L(0); PG8_BAR; PG8_MMA(1, 0, At, B0); PG8_MMA(1, 1, At, B1); PG8_BAR; PG8_SCHED;
;             PG8_LDB(B0, 1, 0); PG8_LDB(B1, 1, 1); PG8_SCHED; PG8_LDA(At, 1, 0); PG8_STAGE(PG8_SA(0, 1), a2 + hstepA, voffA);
;             PG8_WAIT_V(8); PG8_WAIT_L(0); PG8_BAR; PG8_MMA(0, 0, At, B0); PG8_MMA(0, 1, At, B1); PG8_BAR; PG8_SCHED;
	s_setprio 1
	s_waitcnt lgkmcnt(0)
	v_mfma_f32_16x16x32_bf16 v[68:71], v[72:75], v[168:171], v[68:71]
	v_mfma_f32_16x16x32_bf16 v[68:71], v[76:79], v[172:175], v[68:71]
	v_mfma_f32_16x16x32_bf16 v[64:67], v[88:91], v[172:175], v[64:67]
	v_mfma_f32_16x16x32_bf16 v[64:67], v[80:83], v[168:171], v[64:67]
	v_mfma_f32_16x16x32_bf16 v[48:51], v[80:83], v[176:179], v[48:51]
	v_mfma_f32_16x16x32_bf16 v[48:51], v[88:91], v[186:189], v[48:51]
	v_mfma_f32_16x16x32_bf16 v[52:55], v[76:79], v[186:189], v[52:55]
	v_mfma_f32_16x16x32_bf16 v[52:55], v[72:75], v[176:179], v[52:55]
	v_mfma_f32_16x16x32_bf16 v[34:37], v[72:75], v[200:203], v[36:39]
	v_mfma_f32_16x16x32_bf16 v[34:37], v[76:79], v[204:207], v[34:37]
	v_mfma_f32_16x16x32_bf16 v[26:29], v[88:91], v[204:207], v[26:29]
	v_mfma_f32_16x16x32_bf16 v[26:29], v[80:83], v[200:203], v[26:29]
	v_mfma_f32_16x16x32_bf16 v[10:13], v[80:83], v[208:211], v[10:13]
	v_mfma_f32_16x16x32_bf16 v[10:13], v[88:91], v[212:215], v[10:13]
	v_mfma_f32_16x16x32_bf16 v[14:17], v[76:79], v[212:215], v[14:17]
	v_mfma_f32_16x16x32_bf16 v[14:17], v[72:75], v[208:211], v[14:17]
	s_setprio 0
	s_setprio 1
	v_mfma_f32_16x16x32_bf16 v[60:63], v[152:155], v[168:171], v[60:63]
	v_mfma_f32_16x16x32_bf16 v[60:63], v[156:159], v[172:175], v[60:63]
	v_mfma_f32_16x16x32_bf16 v[56:59], v[164:167], v[172:175], v[56:59]
	v_mfma_f32_16x16x32_bf16 v[56:59], v[160:163], v[168:171], v[56:59]
	v_mfma_f32_16x16x32_bf16 v[38:41], v[160:163], v[176:179], v[40:43]
	v_mfma_f32_16x16x32_bf16 v[40:43], v[164:167], v[186:189], v[38:41]
	v_mfma_f32_16x16x32_bf16 v[44:47], v[156:159], v[186:189], v[44:47]
	v_mfma_f32_16x16x32_bf16 v[44:47], v[152:155], v[176:179], v[44:47]
	v_mfma_f32_16x16x32_bf16 v[22:25], v[152:155], v[200:203], v[22:25]
	v_mfma_f32_16x16x32_bf16 v[22:25], v[156:159], v[204:207], v[22:25]
	v_mfma_f32_16x16x32_bf16 v[18:21], v[164:167], v[204:207], v[18:21]
	v_mfma_f32_16x16x32_bf16 v[18:21], v[160:163], v[200:203], v[18:21]
	v_mfma_f32_16x16x32_bf16 v[2:5], v[160:163], v[208:211], v[2:5]
	v_mfma_f32_16x16x32_bf16 v[2:5], v[164:167], v[212:215], v[2:5]
	v_mfma_f32_16x16x32_bf16 v[6:9], v[156:159], v[212:215], v[6:9]
	v_mfma_f32_16x16x32_bf16 v[6:9], v[152:155], v[208:211], v[6:9]
	s_setprio 0
	s_barrier
	s_add_i32 s27, 0, 0x18000
	v_add_u32_e32 v32, s27, v239
	s_add_i32 s33, 0, 0x1c000
	ds_read_b128 v[72:75], v32
	ds_read_b128 v[76:79], v32 offset:1024
	ds_read_b128 v[80:83], v32 offset:2048
	ds_read_b128 v[88:91], v32 offset:3072
	v_add_u32_e32 v32, s33, v239
	ds_read_b128 v[152:155], v32
	ds_read_b128 v[156:159], v32 offset:1024
	ds_read_b128 v[160:163], v32 offset:2048
	ds_read_b128 v[164:167], v32 offset:3072
	s_add_u32 s28, s92, 0x200000
	s_addc_u32 s29, s93, 0
	s_mov_b32 m0, s42
	ds_read_b128 v[168:171], v251 offset:32768
	ds_read_b128 v[172:175], v251 offset:33792
	ds_read_b128 v[176:179], v251 offset:34816
	ds_read_b128 v[186:189], v251 offset:35840
	ds_read_b128 v[200:203], v251 offset:36864
	ds_read_b128 v[204:207], v251 offset:37888
	ds_read_b128 v[208:211], v251 offset:38912
	ds_read_b128 v[212:215], v251 offset:39936
	global_load_lds_dwordx4 v30, s[28:29]
	s_mov_b32 m0, s41
	s_nop 0
	global_load_lds_dwordx4 v180, s[28:29]
	s_waitcnt vmcnt(8)
	s_waitcnt lgkmcnt(0)
	s_barrier
	s_setprio 1
	s_waitcnt lgkmcnt(0)
	v_mfma_f32_16x16x32_bf16 v[84:87], v[72:75], v[168:171], v[84:87]
	v_mfma_f32_16x16x32_bf16 v[84:87], v[76:79], v[172:175], v[84:87]
	v_mfma_f32_16x16x32_bf16 v[148:151], v[88:91], v[172:175], v[148:151]
	v_mfma_f32_16x16x32_bf16 v[148:151], v[80:83], v[168:171], v[148:151]
	v_mfma_f32_16x16x32_bf16 v[132:135], v[80:83], v[176:179], v[132:135]
	v_mfma_f32_16x16x32_bf16 v[132:135], v[88:91], v[186:189], v[132:135]
	v_mfma_f32_16x16x32_bf16 v[136:139], v[76:79], v[186:189], v[136:139]
	v_mfma_f32_16x16x32_bf16 v[136:139], v[72:75], v[176:179], v[136:139]
	v_mfma_f32_16x16x32_bf16 v[120:123], v[72:75], v[200:203], v[120:123]
	v_mfma_f32_16x16x32_bf16 v[120:123], v[76:79], v[204:207], v[120:123]
	v_mfma_f32_16x16x32_bf16 v[116:119], v[88:91], v[204:207], v[116:119]
	v_mfma_f32_16x16x32_bf16 v[116:119], v[80:83], v[200:203], v[116:119]
	v_mfma_f32_16x16x32_bf16 v[100:103], v[80:83], v[208:211], v[100:103]
	v_mfma_f32_16x16x32_bf16 v[100:103], v[88:91], v[212:215], v[100:103]
	v_mfma_f32_16x16x32_bf16 v[104:107], v[76:79], v[212:215], v[104:107]
	v_mfma_f32_16x16x32_bf16 v[104:107], v[72:75], v[208:211], v[104:107]
	s_setprio 0
	s_setprio 1
	v_mfma_f32_16x16x32_bf16 v[144:147], v[152:155], v[168:171], v[144:147]
	v_mfma_f32_16x16x32_bf16 v[144:147], v[156:159], v[172:175], v[144:147]
	v_mfma_f32_16x16x32_bf16 v[140:143], v[164:167], v[172:175], v[140:143]
	v_mfma_f32_16x16x32_bf16 v[140:143], v[160:163], v[168:171], v[140:143]
	v_mfma_f32_16x16x32_bf16 v[124:127], v[160:163], v[176:179], v[124:127]
	v_mfma_f32_16x16x32_bf16 v[124:127], v[164:167], v[186:189], v[124:127]
	v_mfma_f32_16x16x32_bf16 v[128:131], v[156:159], v[186:189], v[128:131]
	v_mfma_f32_16x16x32_bf16 v[128:131], v[152:155], v[176:179], v[128:131]
	v_mfma_f32_16x16x32_bf16 v[112:115], v[152:155], v[200:203], v[112:115]
	v_mfma_f32_16x16x32_bf16 v[112:115], v[156:159], v[204:207], v[112:115]
	v_mfma_f32_16x16x32_bf16 v[108:111], v[164:167], v[204:207], v[108:111]
	v_mfma_f32_16x16x32_bf16 v[108:111], v[160:163], v[200:203], v[108:111]
	v_mfma_f32_16x16x32_bf16 v[92:95], v[160:163], v[208:211], v[92:95]
	v_mfma_f32_16x16x32_bf16 v[92:95], v[164:167], v[212:215], v[92:95]
	v_mfma_f32_16x16x32_bf16 v[96:99], v[156:159], v[212:215], v[96:99]
	v_mfma_f32_16x16x32_bf16 v[96:99], v[152:155], v[208:211], v[96:99]
	s_setprio 0
	s_barrier
; #define PG8_STAGE(bufoff, gbase, voff) do { _Pragma("unroll") for (int _i = 0; _i < 2; ++_i) \
;         __builtin_amdgcn_global_load_lds((const unsigned*)((const char*)(gbase) + (voff)[_i]), (PG8_LAS unsigned*)(lds + (bufoff) + ldsw + _i * 8192), 16, 0, 0); } while (0)
; #define PG8_LDA(dst, b, h) do { _Pragma("unroll") for (int m = 0; m < 4; ++m) _Pragma("unroll") for (int k = 0; k < 2; ++k) dst[m][k] = *(const PG8_LAS bf16x8*)(lds + PG8_SA(b, h) + aoff + m * 2048 + k * 1024); } while (0)
; #define PG8_MMA(ai, bj, At, Bt) do { __builtin_amdgcn_s_setprio(1); _Pragma("unroll") for (int m = 0; m < 4; ++m) _Pragma("unroll") for (int n = 0; n < 2; ++n) _Pragma("unroll") for (int k = 0; k < 2; ++k) \
;         acc[ai][bj][m][n] = __builtin_amdgcn_mfma_f32_16x16x32_bf16(Bt[n][k], At[m][k], acc[ai][bj][m][n], 0, 0, 0); __builtin_amdgcn_s_setprio(0); } while (0)
; #define PG8_WAIT_V(n) asm volatile("s_waitcnt vmcnt(" #n ")" ::: "memory")
; #define PG8_WAIT_L(n) asm volatile("s_waitcnt lgkmcnt(" #n ")" ::: "memory")
; #define PG8_BAR __builtin_amdgcn_s_barrier()
; #define PG8_SCHED __builtin_amdgcn_sched_barrier(0)
;     ...
;         for (int t = 0; t < nt; t += 2) {
;             const bool last = (t == nt - 2);
;             const char* a1 = cA + (size_t)(t + 1) * kstep;
;             const char* a2 = last ? nA : cA + (size_t)(t + 2) * kstep; const char* b2 = last ? nB : cB + (size_t)(t + 2) * kstep;
;     ...
;             PG8_LDA(At, 1, 1); PG8_STAGE(PG8_SB(1, 0), b3, voffB); PG8_STAGE(PG8_SB(1, 1), b3 + hstep, voffB); PG8_STAGE(PG8_SA(1, 0), a3, voffA);
;             PG8_WAIT_V(8); PG8_WAIT_L(0); PG8_BAR; PG8_MMA(1, 0, At, B0); PG8_MMA(1, 1, At, B1); PG8_BAR; PG8_SCHED;
	s_add_i32 s27, s27, s3
	v_lshl_add_u64 v[38:39], v[190:191], 0, s[64:65]
	s_mov_b32 m0, s27
	ds_read_b128 v[168:171], v251 offset:49152
	ds_read_b128 v[172:175], v251 offset:50176
	ds_read_b128 v[176:179], v251 offset:51200
	ds_read_b128 v[186:189], v251 offset:52224
	ds_read_b128 v[200:203], v251 offset:53248
	ds_read_b128 v[204:207], v251 offset:54272
	ds_read_b128 v[208:211], v251 offset:55296
	ds_read_b128 v[212:215], v251 offset:56320
	global_load_lds_dwordx4 v[38:39], off
	s_add_i32 m0, s27, 0x2000
	s_add_u32 s28, s38, 0x200080
	v_lshl_add_u64 v[38:39], v[216:217], 0, s[64:65]
	s_addc_u32 s29, s39, 0
	s_add_i32 s27, s33, s3
	global_load_lds_dwordx4 v[38:39], off
	s_mov_b32 m0, s27
	s_nop 0
	global_load_lds_dwordx4 v30, s[28:29]
	s_add_i32 m0, s27, 0x2000
	s_nop 0
	global_load_lds_dwordx4 v180, s[28:29]
	v_lshl_add_u64 v[38:39], v[218:219], 0, s[64:65]
	s_mov_b32 m0, s53
	s_nop 0
	global_load_lds_dwordx4 v[38:39], off
	v_lshl_add_u64 v[38:39], v[220:221], 0, s[64:65]
	s_mov_b32 m0, s10
	s_nop 0
	global_load_lds_dwordx4 v[38:39], off
	s_waitcnt vmcnt(8)
	s_waitcnt lgkmcnt(0)
	s_barrier
	s_setprio 1
	s_waitcnt lgkmcnt(0)
	v_mfma_f32_16x16x32_bf16 v[68:71], v[72:75], v[168:171], v[68:71]
	v_mfma_f32_16x16x32_bf16 v[68:71], v[76:79], v[172:175], v[68:71]
	v_mfma_f32_16x16x32_bf16 v[64:67], v[88:91], v[172:175], v[64:67]
	v_mfma_f32_16x16x32_bf16 v[64:67], v[80:83], v[168:171], v[64:67]
	v_mfma_f32_16x16x32_bf16 v[48:51], v[80:83], v[176:179], v[48:51]
	v_mfma_f32_16x16x32_bf16 v[48:51], v[88:91], v[186:189], v[48:51]
	v_mfma_f32_16x16x32_bf16 v[52:55], v[76:79], v[186:189], v[52:55]
	v_mfma_f32_16x16x32_bf16 v[52:55], v[72:75], v[176:179], v[52:55]
	v_mfma_f32_16x16x32_bf16 v[34:37], v[72:75], v[200:203], v[34:37]
	v_mfma_f32_16x16x32_bf16 v[36:39], v[76:79], v[204:207], v[34:37]
	v_mfma_f32_16x16x32_bf16 v[26:29], v[88:91], v[204:207], v[26:29]
	v_mfma_f32_16x16x32_bf16 v[26:29], v[80:83], v[200:203], v[26:29]
	v_mfma_f32_16x16x32_bf16 v[10:13], v[80:83], v[208:211], v[10:13]
	v_mfma_f32_16x16x32_bf16 v[10:13], v[88:91], v[212:215], v[10:13]
	v_mfma_f32_16x16x32_bf16 v[14:17], v[76:79], v[212:215], v[14:17]
	v_mfma_f32_16x16x32_bf16 v[14:17], v[72:75], v[208:211], v[14:17]
	s_setprio 0
	s_setprio 1
	v_mfma_f32_16x16x32_bf16 v[60:63], v[152:155], v[168:171], v[60:63]
	v_mfma_f32_16x16x32_bf16 v[60:63], v[156:159], v[172:175], v[60:63]
	v_mfma_f32_16x16x32_bf16 v[56:59], v[164:167], v[172:175], v[56:59]
	v_mfma_f32_16x16x32_bf16 v[56:59], v[160:163], v[168:171], v[56:59]
	v_mfma_f32_16x16x32_bf16 v[40:43], v[160:163], v[176:179], v[40:43]
	v_mfma_f32_16x16x32_bf16 v[40:43], v[164:167], v[186:189], v[40:43]
	v_mfma_f32_16x16x32_bf16 v[44:47], v[156:159], v[186:189], v[44:47]
	v_mfma_f32_16x16x32_bf16 v[44:47], v[152:155], v[176:179], v[44:47]
	v_mfma_f32_16x16x32_bf16 v[22:25], v[152:155], v[200:203], v[22:25]
	v_mfma_f32_16x16x32_bf16 v[22:25], v[156:159], v[204:207], v[22:25]
	v_mfma_f32_16x16x32_bf16 v[18:21], v[164:167], v[204:207], v[18:21]
	v_mfma_f32_16x16x32_bf16 v[18:21], v[160:163], v[200:203], v[18:21]
	v_mfma_f32_16x16x32_bf16 v[2:5], v[160:163], v[208:211], v[2:5]
	v_mfma_f32_16x16x32_bf16 v[2:5], v[164:167], v[212:215], v[2:5]
	v_mfma_f32_16x16x32_bf16 v[6:9], v[156:159], v[212:215], v[6:9]
	v_mfma_f32_16x16x32_bf16 v[6:9], v[152:155], v[208:211], v[6:9]
	s_setprio 0
	s_barrier
	s_add_i32 s27, s25, 2
	s_add_u32 s9, s9, 0x100
	s_addc_u32 s23, s23, 0
	s_cmp_ge_i32 s25, s40
	s_mov_b64 s[28:29], s[30:31]
	s_mov_b32 s25, s27
	s_cbranch_scc0 .LBB0_1454
	s_and_b64 vcc, exec, s[16:17]
	s_cbranch_vccz .LBB0_1457
	s_barrier
